# c10_inline_fastpaths
# baseline (speedup 1.0000x reference)
.LBB0_871:
	s_add_i32 s80, s75, -3
	s_lshl_b32 s76, s74, 14
	s_add_i32 s8, s69, s76
	v_lshl_add_u64 v[2:3], v[226:227], 0, s[34:35]
	s_mov_b32 m0, s8
	s_nop 0
	global_load_lds_dwordx4 v[2:3], off
	s_add_i32 m0, s8, 0x2000
	s_mul_i32 s8, s60, 0x6300
	s_add_i32 s61, s68, s8
	global_load_lds_dwordx4 v[226:227], off
	s_add_i32 m0, s61, 0xc000
	s_add_i32 s8, s75, -1
	s_cmp_lt_u32 s8, s77
	s_cselect_b32 s8, s8, s73
	s_lshl_b32 s8, s8, 6
	s_lshl_b64 s[58:59], s[8:9], 12
	v_lshl_add_u64 v[2:3], v[218:219], 0, s[58:59]
	global_load_lds_dwordx4 v[2:3], off
	v_lshl_add_u64 v[2:3], v[2:3], 0, s[12:13]
	s_add_i32 m0, s61, 0xe100
	s_lshl_b64 s[82:83], s[8:9], 7
	global_load_lds_dwordx4 v[2:3], off
	v_lshl_add_u64 v[2:3], v[224:225], 0, s[82:83]
	s_add_i32 m0, s61, 0x10200
	s_nop 0
	global_load_lds_dwordx4 v[2:3], off
	s_mul_i32 s8, s79, 0x6300
	s_add_i32 s8, s8, 0
	v_add_u32_e32 v0, s8, v237
	ds_read_b128 v[2:5], v0 offset:49152
	ds_read_b128 v[6:9], v0 offset:50176
	s_waitcnt lgkmcnt(0)
	v_mfma_f32_32x32x16_bf16 v[112:127], v[2:5], v[188:191], 0
	v_mfma_f32_32x32x16_bf16 v[128:143], v[6:9], v[188:191], 0
	ds_read_b128 v[2:5], v0 offset:51264
	ds_read_b128 v[6:9], v0 offset:52288
	s_waitcnt lgkmcnt(0)
	v_mfma_f32_32x32x16_bf16 v[112:127], v[2:5], v[184:187], v[112:127]
	v_mfma_f32_32x32x16_bf16 v[128:143], v[6:9], v[184:187], v[128:143]
	ds_read_b128 v[2:5], v0 offset:53376
	ds_read_b128 v[6:9], v0 offset:54400
	s_waitcnt lgkmcnt(0)
	v_mfma_f32_32x32x16_bf16 v[112:127], v[2:5], v[180:183], v[112:127]
	v_mfma_f32_32x32x16_bf16 v[128:143], v[6:9], v[180:183], v[128:143]
	ds_read_b128 v[2:5], v0 offset:55488
	ds_read_b128 v[6:9], v0 offset:56512
	s_waitcnt lgkmcnt(0)
	v_mfma_f32_32x32x16_bf16 v[112:127], v[2:5], v[176:179], v[112:127]
	v_mfma_f32_32x32x16_bf16 v[128:143], v[6:9], v[176:179], v[128:143]
	ds_read_b128 v[2:5], v0 offset:57600
	ds_read_b128 v[6:9], v0 offset:58624
	s_waitcnt lgkmcnt(0)
	v_mfma_f32_32x32x16_bf16 v[112:127], v[2:5], v[172:175], v[112:127]
	v_mfma_f32_32x32x16_bf16 v[128:143], v[6:9], v[172:175], v[128:143]
	ds_read_b128 v[2:5], v0 offset:59712
	ds_read_b128 v[6:9], v0 offset:60736
	s_waitcnt lgkmcnt(0)
	v_mfma_f32_32x32x16_bf16 v[112:127], v[2:5], v[168:171], v[112:127]
	v_mfma_f32_32x32x16_bf16 v[128:143], v[6:9], v[168:171], v[128:143]
	ds_read_b128 v[2:5], v0 offset:61824
	ds_read_b128 v[6:9], v0 offset:62848
	s_waitcnt lgkmcnt(0)
	v_mfma_f32_32x32x16_bf16 v[112:127], v[2:5], v[164:167], v[112:127]
	v_mfma_f32_32x32x16_bf16 v[128:143], v[6:9], v[164:167], v[128:143]
	ds_read_b128 v[2:5], v0 offset:63936
	ds_read_b128 v[6:9], v0 offset:64960
	v_add_u32_e32 v0, 0xc000, v0
	s_waitcnt lgkmcnt(0)
	v_mfma_f32_32x32x16_bf16 v[112:127], v[2:5], v[160:163], v[112:127]
	ds_read_b128 v[2:5], v0 offset:17920
	ds_read_b128 v[10:13], v0 offset:16896
	v_mfma_f32_32x32x16_bf16 v[128:143], v[6:9], v[160:163], v[128:143]
	ds_read_b128 v[6:9], v0 offset:20032
	ds_read_b128 v[192:195], v0 offset:19008
	ds_read_b128 v[196:199], v0 offset:22144
	ds_read_b128 v[200:203], v0 offset:21120
	ds_read_b128 v[204:207], v0 offset:24256
	ds_read_b128 v[208:211], v0 offset:23232
	v_add_f32_e32 v0, 0, v96
	v_add_f32_e32 v0, v97, v0
	v_add_f32_e32 v0, v98, v0
	v_add_f32_e32 v0, v99, v0
	v_add_f32_e32 v0, v100, v0
	v_add_f32_e32 v0, v101, v0
	s_waitcnt lgkmcnt(0)
	v_mfma_f32_32x32x16_bf16 v[112:127], v[10:13], v[156:159], v[112:127]
	v_add_f32_e32 v0, v102, v0
	v_add_f32_e32 v0, v103, v0
	v_add_f32_e32 v0, v104, v0
	v_add_f32_e32 v0, v105, v0
	v_add_f32_e32 v0, v106, v0
	v_add_f32_e32 v0, v107, v0
	v_add_f32_e32 v0, v108, v0
	v_mfma_f32_32x32x16_bf16 v[128:143], v[2:5], v[156:159], v[128:143]
	v_add_f32_e32 v0, v109, v0
	v_add_f32_e32 v0, v110, v0
	v_add_f32_e32 v0, v111, v0
	v_add_f32_e32 v0, v80, v0
	v_add_f32_e32 v0, v81, v0
	v_add_f32_e32 v0, v82, v0
	v_add_f32_e32 v0, v83, v0
	v_mfma_f32_32x32x16_bf16 v[112:127], v[192:195], v[152:155], v[112:127]
	v_add_f32_e32 v0, v84, v0
	v_add_f32_e32 v0, v85, v0
	v_add_f32_e32 v0, v86, v0
	v_add_f32_e32 v0, v87, v0
	v_add_f32_e32 v0, v88, v0
	v_add_f32_e32 v0, v89, v0
	v_add_f32_e32 v0, v90, v0
	v_mfma_f32_32x32x16_bf16 v[128:143], v[6:9], v[152:155], v[128:143]
	v_add_f32_e32 v0, v91, v0
	v_add_f32_e32 v0, v92, v0
	v_add_f32_e32 v0, v93, v0
	v_add_f32_e32 v0, v94, v0
	v_add_f32_e32 v14, v95, v0
	v_mov_b32_e32 v15, v14
	s_nop 1
	v_permlane32_swap_b32_e32 v14, v15
	v_mfma_f32_32x32x16_bf16 v[112:127], v[200:203], v[148:151], v[112:127]
	v_cvt_pk_bf16_f32 v192, v96, v97
	v_cvt_pk_bf16_f32 v193, v98, v99
	v_cvt_pk_bf16_f32 v194, v100, v101
	v_cvt_pk_bf16_f32 v195, v102, v103
	v_cvt_pk_bf16_f32 v10, v104, v105
	v_cvt_pk_bf16_f32 v11, v106, v107
	v_cvt_pk_bf16_f32 v12, v108, v109
	v_mfma_f32_32x32x16_bf16 v[128:143], v[196:199], v[148:151], v[128:143]
	v_cvt_pk_bf16_f32 v13, v110, v111
	v_cvt_pk_bf16_f32 v6, v80, v81
	v_cvt_pk_bf16_f32 v7, v82, v83
	v_cvt_pk_bf16_f32 v8, v84, v85
	v_cvt_pk_bf16_f32 v9, v86, v87
	v_cvt_pk_bf16_f32 v2, v88, v89
	v_cvt_pk_bf16_f32 v3, v90, v91
	v_mfma_f32_32x32x16_bf16 v[112:127], v[208:211], v[144:147], v[112:127]
	v_cvt_pk_bf16_f32 v4, v92, v93
	v_cvt_pk_bf16_f32 v5, v94, v95
	v_mfma_f32_32x32x16_bf16 v[128:143], v[204:207], v[144:147], v[128:143]
	s_cmp_gt_i32 s80, s72
	s_cbranch_scc1 .Lold_mla_odd
	v_lshl_add_u32 v0, s60, 14, v235
	ds_read_b64_tr_b16 v[208:209], v0 offset:0
	ds_read_b64_tr_b16 v[210:211], v0 offset:0x800
	ds_read_b64_tr_b16 v[204:205], v0 offset:0x1000
	ds_read_b64_tr_b16 v[206:207], v0 offset:0x1800
	ds_read_b64_tr_b16 v[200:201], v0 offset:0x2000
	ds_read_b64_tr_b16 v[202:203], v0 offset:0x2800
	ds_read_b64_tr_b16 v[196:197], v0 offset:0x3000
	ds_read_b64_tr_b16 v[198:199], v0 offset:0x3800
	s_nop 1
	v_max3_f32 v245, v112, v113, v114
	v_max3_f32 v246, v128, v129, v130
	v_max3_f32 v245, v245, v115, v116
	v_max3_f32 v246, v246, v131, v132
	v_max3_f32 v245, v245, v117, v118
	v_max3_f32 v246, v246, v133, v134
	v_max3_f32 v245, v245, v119, v120
	v_max3_f32 v246, v246, v135, v136
	v_max3_f32 v245, v245, v121, v122
	v_max3_f32 v246, v246, v137, v138
	v_max3_f32 v245, v245, v123, v124
	v_max3_f32 v246, v246, v139, v140
	v_max3_f32 v245, v245, v125, v126
	v_max3_f32 v246, v246, v141, v142
	v_max_f32_e32 v245, v245, v127
	v_max_f32_e32 v246, v246, v143
	v_max_f32_e32 v245, v245, v246
	v_mov_b32_e32 v246, v245
	s_nop 1
	v_permlane32_swap_b32_e32 v245, v246
	v_max_f32_e32 v245, v245, v246
	v_sub_f32_e32 v246, v245, v236
	v_cmp_ge_f32_e32 vcc, s29, v246
	s_cmp_eq_u64 vcc, exec
	v_mov_b32_e32 v240, 1.0
	s_cbranch_scc0 .Lfm_odd_ev
.Lfm_odd_exp:
	v_sub_f32_e32 v96, v112, v236
	v_sub_f32_e32 v97, v113, v236
	ds_read_b64_tr_b16 v[112:113], v0 offset:0x200
	v_sub_f32_e32 v98, v114, v236
	v_sub_f32_e32 v99, v115, v236
	ds_read_b64_tr_b16 v[114:115], v0 offset:0xa00
	v_sub_f32_e32 v100, v116, v236
	v_sub_f32_e32 v101, v117, v236
	ds_read_b64_tr_b16 v[116:117], v0 offset:0x1200
	v_sub_f32_e32 v102, v118, v236
	v_sub_f32_e32 v103, v119, v236
	ds_read_b64_tr_b16 v[118:119], v0 offset:0x1a00
	v_sub_f32_e32 v104, v120, v236
	v_sub_f32_e32 v105, v121, v236
	ds_read_b64_tr_b16 v[120:121], v0 offset:0x2200
	v_sub_f32_e32 v106, v122, v236
	v_sub_f32_e32 v107, v123, v236
	ds_read_b64_tr_b16 v[122:123], v0 offset:0x2a00
	v_sub_f32_e32 v108, v124, v236
	v_sub_f32_e32 v109, v125, v236
	ds_read_b64_tr_b16 v[124:125], v0 offset:0x3200
	v_sub_f32_e32 v110, v126, v236
	v_sub_f32_e32 v111, v127, v236
	ds_read_b64_tr_b16 v[126:127], v0 offset:0x3a00
	v_sub_f32_e32 v80, v128, v236
	v_sub_f32_e32 v81, v129, v236
	v_sub_f32_e32 v82, v130, v236
	v_sub_f32_e32 v83, v131, v236
	s_waitcnt lgkmcnt(8)
	v_mfma_f32_32x32x16_bf16 v[64:79], v[192:195], v[208:211], v[64:79]
	v_exp_f32_e32 v96, v96
	v_exp_f32_e32 v80, v80
	v_sub_f32_e32 v84, v132, v236
	v_sub_f32_e32 v85, v133, v236
	v_sub_f32_e32 v86, v134, v236
	v_mfma_f32_32x32x16_bf16 v[64:79], v[10:13], v[204:207], v[64:79]
	v_exp_f32_e32 v97, v97
	v_exp_f32_e32 v81, v81
	v_sub_f32_e32 v87, v135, v236
	v_sub_f32_e32 v88, v136, v236
	v_sub_f32_e32 v89, v137, v236
	v_mfma_f32_32x32x16_bf16 v[64:79], v[6:9], v[200:203], v[64:79]
	v_exp_f32_e32 v98, v98
	v_exp_f32_e32 v82, v82
	v_sub_f32_e32 v90, v138, v236
	v_sub_f32_e32 v91, v139, v236
	v_sub_f32_e32 v92, v140, v236
	v_mfma_f32_32x32x16_bf16 v[64:79], v[2:5], v[196:199], v[64:79]
	v_exp_f32_e32 v99, v99
	v_exp_f32_e32 v83, v83
	v_sub_f32_e32 v93, v141, v236
	v_sub_f32_e32 v94, v142, v236
	v_sub_f32_e32 v95, v143, v236
	ds_read_b64_tr_b16 v[128:129], v0 offset:0x400
	ds_read_b64_tr_b16 v[130:131], v0 offset:0xc00
	ds_read_b64_tr_b16 v[132:133], v0 offset:0x1400
	ds_read_b64_tr_b16 v[134:135], v0 offset:0x1c00
	ds_read_b64_tr_b16 v[136:137], v0 offset:0x2400
	ds_read_b64_tr_b16 v[138:139], v0 offset:0x2c00
	ds_read_b64_tr_b16 v[140:141], v0 offset:0x3400
	ds_read_b64_tr_b16 v[142:143], v0 offset:0x3c00
	s_waitcnt lgkmcnt(8)
	v_mfma_f32_32x32x16_bf16 v[48:63], v[192:195], v[112:115], v[48:63]
	v_exp_f32_e32 v100, v100
	v_exp_f32_e32 v84, v84
	v_mfma_f32_32x32x16_bf16 v[48:63], v[10:13], v[116:119], v[48:63]
	v_exp_f32_e32 v101, v101
	v_exp_f32_e32 v85, v85
	v_mfma_f32_32x32x16_bf16 v[48:63], v[6:9], v[120:123], v[48:63]
	v_exp_f32_e32 v102, v102
	v_exp_f32_e32 v86, v86
	v_mfma_f32_32x32x16_bf16 v[48:63], v[2:5], v[124:127], v[48:63]
	v_exp_f32_e32 v103, v103
	v_exp_f32_e32 v87, v87
	ds_read_b64_tr_b16 v[112:113], v0 offset:0x600
	ds_read_b64_tr_b16 v[114:115], v0 offset:0xe00
	ds_read_b64_tr_b16 v[116:117], v0 offset:0x1600
	ds_read_b64_tr_b16 v[118:119], v0 offset:0x1e00
	ds_read_b64_tr_b16 v[120:121], v0 offset:0x2600
	ds_read_b64_tr_b16 v[122:123], v0 offset:0x2e00
	ds_read_b64_tr_b16 v[124:125], v0 offset:0x3600
	ds_read_b64_tr_b16 v[126:127], v0 offset:0x3e00
	s_waitcnt lgkmcnt(8)
	v_mfma_f32_32x32x16_bf16 v[32:47], v[192:195], v[128:131], v[32:47]
	v_exp_f32_e32 v104, v104
	v_exp_f32_e32 v88, v88
	v_mfma_f32_32x32x16_bf16 v[32:47], v[10:13], v[132:135], v[32:47]
	v_exp_f32_e32 v105, v105
	v_exp_f32_e32 v89, v89
	v_mfma_f32_32x32x16_bf16 v[32:47], v[6:9], v[136:139], v[32:47]
	v_exp_f32_e32 v106, v106
	v_exp_f32_e32 v90, v90
	v_mfma_f32_32x32x16_bf16 v[32:47], v[2:5], v[140:143], v[32:47]
	v_exp_f32_e32 v107, v107
	v_exp_f32_e32 v91, v91
	s_waitcnt lgkmcnt(0)
	v_mfma_f32_32x32x16_bf16 v[16:31], v[192:195], v[112:115], v[16:31]
	v_exp_f32_e32 v108, v108
	v_exp_f32_e32 v92, v92
	v_mfma_f32_32x32x16_bf16 v[16:31], v[10:13], v[116:119], v[16:31]
	v_exp_f32_e32 v109, v109
	v_exp_f32_e32 v93, v93
	v_mfma_f32_32x32x16_bf16 v[16:31], v[6:9], v[120:123], v[16:31]
	v_exp_f32_e32 v110, v110
	v_exp_f32_e32 v94, v94
	v_mfma_f32_32x32x16_bf16 v[16:31], v[2:5], v[124:127], v[16:31]
	v_exp_f32_e32 v111, v111
	v_exp_f32_e32 v95, v95
	v_cmp_gt_f32_e32 vcc, 1.0, v240
	s_cbranch_vccnz .Lresc_mla_odd_blk
.LBB0_876:
	s_waitcnt vmcnt(0)
	s_add_i32 s60, s74, 1
	s_cmp_lg_u32 s74, 2
	s_cselect_b32 s81, s60, 0
	s_waitcnt vmcnt(0)
	s_barrier
	s_lshl_b32 s78, s81, 14
	s_add_i32 s60, s69, s78
	v_lshl_add_u64 v[2:3], v[222:223], 0, s[58:59]
	v_lshl_add_u64 v[4:5], v[2:3], 0, s[14:15]
	s_mov_b32 m0, s60
	s_add_i32 s8, s8, s70
	global_load_lds_dwordx4 v[4:5], off
	v_lshl_add_u64 v[2:3], v[2:3], 0, s[16:17]
	s_add_i32 m0, s60, 0x2000
	s_add_i32 s82, s8, s71
	global_load_lds_dwordx4 v[2:3], off
	s_add_i32 m0, s82, 0xc000
	s_cmp_ge_u32 s75, s77
	s_cselect_b64 s[58:59], -1, 0
	s_cmp_lt_u32 s75, s77
	s_cselect_b32 s8, s75, s73
	s_lshl_b32 s8, s8, 6
	s_lshl_b64 s[60:61], s[8:9], 12
	v_lshl_add_u64 v[2:3], v[218:219], 0, s[60:61]
	global_load_lds_dwordx4 v[2:3], off
	v_lshl_add_u64 v[2:3], v[2:3], 0, s[12:13]
	s_add_i32 m0, s82, 0xe100
	s_lshl_b64 s[60:61], s[8:9], 7
	global_load_lds_dwordx4 v[2:3], off
	v_lshl_add_u64 v[2:3], v[224:225], 0, s[60:61]
	s_add_i32 m0, s82, 0x10200
	s_nop 0
	global_load_lds_dwordx4 v[2:3], off
	s_mul_i32 s8, s74, 0x6300
	v_add_u32_e32 v0, s8, v238
	ds_read_b128 v[2:5], v0 offset:49152
	ds_read_b128 v[6:9], v0 offset:50176
	s_waitcnt lgkmcnt(0)
	v_mfma_f32_32x32x16_bf16 v[112:127], v[2:5], v[188:191], 0
	v_mfma_f32_32x32x16_bf16 v[128:143], v[6:9], v[188:191], 0
	ds_read_b128 v[2:5], v0 offset:51264
	ds_read_b128 v[6:9], v0 offset:52288
	s_waitcnt lgkmcnt(0)
	v_mfma_f32_32x32x16_bf16 v[112:127], v[2:5], v[184:187], v[112:127]
	v_mfma_f32_32x32x16_bf16 v[128:143], v[6:9], v[184:187], v[128:143]
	ds_read_b128 v[2:5], v0 offset:53376
	ds_read_b128 v[6:9], v0 offset:54400
	s_waitcnt lgkmcnt(0)
	v_mfma_f32_32x32x16_bf16 v[112:127], v[2:5], v[180:183], v[112:127]
	v_mfma_f32_32x32x16_bf16 v[128:143], v[6:9], v[180:183], v[128:143]
	ds_read_b128 v[2:5], v0 offset:55488
	ds_read_b128 v[6:9], v0 offset:56512
	s_waitcnt lgkmcnt(0)
	v_mfma_f32_32x32x16_bf16 v[112:127], v[2:5], v[176:179], v[112:127]
	v_mfma_f32_32x32x16_bf16 v[128:143], v[6:9], v[176:179], v[128:143]
	ds_read_b128 v[2:5], v0 offset:57600
	ds_read_b128 v[6:9], v0 offset:58624
	s_waitcnt lgkmcnt(0)
	v_mfma_f32_32x32x16_bf16 v[112:127], v[2:5], v[172:175], v[112:127]
	v_mfma_f32_32x32x16_bf16 v[128:143], v[6:9], v[172:175], v[128:143]
	ds_read_b128 v[2:5], v0 offset:59712
	ds_read_b128 v[6:9], v0 offset:60736
	s_waitcnt lgkmcnt(0)
	v_mfma_f32_32x32x16_bf16 v[112:127], v[2:5], v[168:171], v[112:127]
	v_mfma_f32_32x32x16_bf16 v[128:143], v[6:9], v[168:171], v[128:143]
	ds_read_b128 v[2:5], v0 offset:61824
	ds_read_b128 v[6:9], v0 offset:62848
	s_waitcnt lgkmcnt(0)
	v_mfma_f32_32x32x16_bf16 v[112:127], v[2:5], v[164:167], v[112:127]
	v_mfma_f32_32x32x16_bf16 v[128:143], v[6:9], v[164:167], v[128:143]
	ds_read_b128 v[2:5], v0 offset:63936
	ds_read_b128 v[6:9], v0 offset:64960
	v_add_u32_e32 v0, 0xc000, v0
	s_waitcnt lgkmcnt(0)
	v_mfma_f32_32x32x16_bf16 v[112:127], v[2:5], v[160:163], v[112:127]
	ds_read_b128 v[2:5], v0 offset:17920
	ds_read_b128 v[10:13], v0 offset:16896
	v_mfma_f32_32x32x16_bf16 v[128:143], v[6:9], v[160:163], v[128:143]
	ds_read_b128 v[6:9], v0 offset:20032
	ds_read_b128 v[192:195], v0 offset:19008
	ds_read_b128 v[196:199], v0 offset:22144
	ds_read_b128 v[200:203], v0 offset:21120
	ds_read_b128 v[204:207], v0 offset:24256
	ds_read_b128 v[208:211], v0 offset:23232
	v_add_f32_e32 v0, 0, v96
	v_add_f32_e32 v0, v97, v0
	v_add_f32_e32 v0, v98, v0
	v_add_f32_e32 v0, v99, v0
	v_add_f32_e32 v0, v100, v0
	v_add_f32_e32 v0, v101, v0
	s_waitcnt lgkmcnt(0)
	v_mfma_f32_32x32x16_bf16 v[112:127], v[10:13], v[156:159], v[112:127]
	v_add_f32_e32 v0, v102, v0
	v_add_f32_e32 v0, v103, v0
	v_add_f32_e32 v0, v104, v0
	v_add_f32_e32 v0, v105, v0
	v_add_f32_e32 v0, v106, v0
	v_add_f32_e32 v0, v107, v0
	v_add_f32_e32 v0, v108, v0
	v_mfma_f32_32x32x16_bf16 v[128:143], v[2:5], v[156:159], v[128:143]
	v_add_f32_e32 v0, v109, v0
	v_add_f32_e32 v0, v110, v0
	v_add_f32_e32 v0, v111, v0
	v_add_f32_e32 v0, v80, v0
	v_add_f32_e32 v0, v81, v0
	v_add_f32_e32 v0, v82, v0
	v_add_f32_e32 v0, v83, v0
	v_mfma_f32_32x32x16_bf16 v[112:127], v[192:195], v[152:155], v[112:127]
	v_add_f32_e32 v0, v84, v0
	v_add_f32_e32 v0, v85, v0
	v_add_f32_e32 v0, v86, v0
	v_add_f32_e32 v0, v87, v0
	v_add_f32_e32 v0, v88, v0
	v_add_f32_e32 v0, v89, v0
	v_add_f32_e32 v0, v90, v0
	v_mfma_f32_32x32x16_bf16 v[128:143], v[6:9], v[152:155], v[128:143]
	v_add_f32_e32 v0, v91, v0
	v_add_f32_e32 v0, v92, v0
	v_add_f32_e32 v0, v93, v0
	v_add_f32_e32 v0, v94, v0
	v_add_f32_e32 v241, v95, v0
	v_mov_b32_e32 v242, v241
	s_nop 1
	v_permlane32_swap_b32_e32 v241, v242
	v_mfma_f32_32x32x16_bf16 v[112:127], v[200:203], v[148:151], v[112:127]
	v_cvt_pk_bf16_f32 v192, v96, v97
	v_cvt_pk_bf16_f32 v193, v98, v99
	v_cvt_pk_bf16_f32 v194, v100, v101
	v_cvt_pk_bf16_f32 v195, v102, v103
	v_cvt_pk_bf16_f32 v10, v104, v105
	v_cvt_pk_bf16_f32 v11, v106, v107
	v_cvt_pk_bf16_f32 v12, v108, v109
	v_mfma_f32_32x32x16_bf16 v[128:143], v[196:199], v[148:151], v[128:143]
	v_cvt_pk_bf16_f32 v13, v110, v111
	v_cvt_pk_bf16_f32 v6, v80, v81
	v_cvt_pk_bf16_f32 v7, v82, v83
	v_cvt_pk_bf16_f32 v8, v84, v85
	v_cvt_pk_bf16_f32 v9, v86, v87
	v_cvt_pk_bf16_f32 v2, v88, v89
	v_cvt_pk_bf16_f32 v3, v90, v91
	v_mfma_f32_32x32x16_bf16 v[112:127], v[208:211], v[144:147], v[112:127]
	v_cvt_pk_bf16_f32 v4, v92, v93
	v_cvt_pk_bf16_f32 v5, v94, v95
	v_mfma_f32_32x32x16_bf16 v[128:143], v[204:207], v[144:147], v[128:143]
	s_cmp_lt_i32 s80, s72
	s_cbranch_scc0 .Lold_mla_even
	v_lshl_add_u32 v243, s79, 14, v235
	ds_read_b64_tr_b16 v[208:209], v243 offset:0
	ds_read_b64_tr_b16 v[210:211], v243 offset:0x800
	ds_read_b64_tr_b16 v[204:205], v243 offset:0x1000
	ds_read_b64_tr_b16 v[206:207], v243 offset:0x1800
	ds_read_b64_tr_b16 v[200:201], v243 offset:0x2000
	ds_read_b64_tr_b16 v[202:203], v243 offset:0x2800
	ds_read_b64_tr_b16 v[196:197], v243 offset:0x3000
	ds_read_b64_tr_b16 v[198:199], v243 offset:0x3800
	s_nop 1
	v_max3_f32 v245, v112, v113, v114
	v_max3_f32 v246, v128, v129, v130
	v_max3_f32 v245, v245, v115, v116
	v_max3_f32 v246, v246, v131, v132
	v_max3_f32 v245, v245, v117, v118
	v_max3_f32 v246, v246, v133, v134
	v_max3_f32 v245, v245, v119, v120
	v_max3_f32 v246, v246, v135, v136
	v_max3_f32 v245, v245, v121, v122
	v_max3_f32 v246, v246, v137, v138
	v_max3_f32 v245, v245, v123, v124
	v_max3_f32 v246, v246, v139, v140
	v_max3_f32 v245, v245, v125, v126
	v_max3_f32 v246, v246, v141, v142
	v_max_f32_e32 v245, v245, v127
	v_max_f32_e32 v246, v246, v143
	v_max_f32_e32 v245, v245, v246
	v_mov_b32_e32 v246, v245
	s_nop 1
	v_permlane32_swap_b32_e32 v245, v246
	v_max_f32_e32 v245, v245, v246
	v_sub_f32_e32 v246, v245, v236
	v_cmp_ge_f32_e32 vcc, s29, v246
	s_cmp_eq_u64 vcc, exec
	v_mov_b32_e32 v0, 1.0
	s_cbranch_scc0 .Lfm_even_ev
.Lfm_even_exp:
	v_sub_f32_e32 v96, v112, v236
	v_sub_f32_e32 v97, v113, v236
	ds_read_b64_tr_b16 v[112:113], v243 offset:0x200
	v_sub_f32_e32 v98, v114, v236
	v_sub_f32_e32 v99, v115, v236
	ds_read_b64_tr_b16 v[114:115], v243 offset:0xa00
	v_sub_f32_e32 v100, v116, v236
	v_sub_f32_e32 v101, v117, v236
	ds_read_b64_tr_b16 v[116:117], v243 offset:0x1200
	v_sub_f32_e32 v102, v118, v236
	v_sub_f32_e32 v103, v119, v236
	ds_read_b64_tr_b16 v[118:119], v243 offset:0x1a00
	v_sub_f32_e32 v104, v120, v236
	v_sub_f32_e32 v105, v121, v236
	ds_read_b64_tr_b16 v[120:121], v243 offset:0x2200
	v_sub_f32_e32 v106, v122, v236
	v_sub_f32_e32 v107, v123, v236
	ds_read_b64_tr_b16 v[122:123], v243 offset:0x2a00
	v_sub_f32_e32 v108, v124, v236
	v_sub_f32_e32 v109, v125, v236
	ds_read_b64_tr_b16 v[124:125], v243 offset:0x3200
	v_sub_f32_e32 v110, v126, v236
	v_sub_f32_e32 v111, v127, v236
	ds_read_b64_tr_b16 v[126:127], v243 offset:0x3a00
	v_sub_f32_e32 v80, v128, v236
	v_sub_f32_e32 v81, v129, v236
	v_sub_f32_e32 v82, v130, v236
	v_sub_f32_e32 v83, v131, v236
	s_waitcnt lgkmcnt(8)
	v_mfma_f32_32x32x16_bf16 v[64:79], v[192:195], v[208:211], v[64:79]
	v_exp_f32_e32 v96, v96
	v_exp_f32_e32 v80, v80
	v_sub_f32_e32 v84, v132, v236
	v_sub_f32_e32 v85, v133, v236
	v_sub_f32_e32 v86, v134, v236
	v_mfma_f32_32x32x16_bf16 v[64:79], v[10:13], v[204:207], v[64:79]
	v_exp_f32_e32 v97, v97
	v_exp_f32_e32 v81, v81
	v_sub_f32_e32 v87, v135, v236
	v_sub_f32_e32 v88, v136, v236
	v_sub_f32_e32 v89, v137, v236
	v_mfma_f32_32x32x16_bf16 v[64:79], v[6:9], v[200:203], v[64:79]
	v_exp_f32_e32 v98, v98
	v_exp_f32_e32 v82, v82
	v_sub_f32_e32 v90, v138, v236
	v_sub_f32_e32 v91, v139, v236
	v_sub_f32_e32 v92, v140, v236
	v_mfma_f32_32x32x16_bf16 v[64:79], v[2:5], v[196:199], v[64:79]
	v_exp_f32_e32 v99, v99
	v_exp_f32_e32 v83, v83
	v_sub_f32_e32 v93, v141, v236
	v_sub_f32_e32 v94, v142, v236
	v_sub_f32_e32 v95, v143, v236
	ds_read_b64_tr_b16 v[128:129], v243 offset:0x400
	ds_read_b64_tr_b16 v[130:131], v243 offset:0xc00
	ds_read_b64_tr_b16 v[132:133], v243 offset:0x1400
	ds_read_b64_tr_b16 v[134:135], v243 offset:0x1c00
	ds_read_b64_tr_b16 v[136:137], v243 offset:0x2400
	ds_read_b64_tr_b16 v[138:139], v243 offset:0x2c00
	ds_read_b64_tr_b16 v[140:141], v243 offset:0x3400
	ds_read_b64_tr_b16 v[142:143], v243 offset:0x3c00
	s_waitcnt lgkmcnt(8)
	v_mfma_f32_32x32x16_bf16 v[48:63], v[192:195], v[112:115], v[48:63]
	v_exp_f32_e32 v100, v100
	v_exp_f32_e32 v84, v84
	v_mfma_f32_32x32x16_bf16 v[48:63], v[10:13], v[116:119], v[48:63]
	v_exp_f32_e32 v101, v101
	v_exp_f32_e32 v85, v85
	v_mfma_f32_32x32x16_bf16 v[48:63], v[6:9], v[120:123], v[48:63]
	v_exp_f32_e32 v102, v102
	v_exp_f32_e32 v86, v86
	v_mfma_f32_32x32x16_bf16 v[48:63], v[2:5], v[124:127], v[48:63]
	v_exp_f32_e32 v103, v103
	v_exp_f32_e32 v87, v87
	ds_read_b64_tr_b16 v[112:113], v243 offset:0x600
	ds_read_b64_tr_b16 v[114:115], v243 offset:0xe00
	ds_read_b64_tr_b16 v[116:117], v243 offset:0x1600
	ds_read_b64_tr_b16 v[118:119], v243 offset:0x1e00
	ds_read_b64_tr_b16 v[120:121], v243 offset:0x2600
	ds_read_b64_tr_b16 v[122:123], v243 offset:0x2e00
	ds_read_b64_tr_b16 v[124:125], v243 offset:0x3600
	ds_read_b64_tr_b16 v[126:127], v243 offset:0x3e00
	s_waitcnt lgkmcnt(8)
	v_mfma_f32_32x32x16_bf16 v[32:47], v[192:195], v[128:131], v[32:47]
	v_exp_f32_e32 v104, v104
	v_exp_f32_e32 v88, v88
	v_mfma_f32_32x32x16_bf16 v[32:47], v[10:13], v[132:135], v[32:47]
	v_exp_f32_e32 v105, v105
	v_exp_f32_e32 v89, v89
	v_mfma_f32_32x32x16_bf16 v[32:47], v[6:9], v[136:139], v[32:47]
	v_exp_f32_e32 v106, v106
	v_exp_f32_e32 v90, v90
	v_mfma_f32_32x32x16_bf16 v[32:47], v[2:5], v[140:143], v[32:47]
	v_exp_f32_e32 v107, v107
	v_exp_f32_e32 v91, v91
	s_waitcnt lgkmcnt(0)
	v_mfma_f32_32x32x16_bf16 v[16:31], v[192:195], v[112:115], v[16:31]
	v_exp_f32_e32 v108, v108
	v_exp_f32_e32 v92, v92
	v_mfma_f32_32x32x16_bf16 v[16:31], v[10:13], v[116:119], v[16:31]
	v_exp_f32_e32 v109, v109
	v_exp_f32_e32 v93, v93
	v_mfma_f32_32x32x16_bf16 v[16:31], v[6:9], v[120:123], v[16:31]
	v_exp_f32_e32 v110, v110
	v_exp_f32_e32 v94, v94
	v_mfma_f32_32x32x16_bf16 v[16:31], v[2:5], v[124:127], v[16:31]
	v_exp_f32_e32 v111, v111
	v_exp_f32_e32 v95, v95
	v_cmp_gt_f32_e32 vcc, 1.0, v0
	s_cbranch_vccnz .Lresc_mla_even_blk

.Lold_mla_odd:
	s_cselect_b64 vcc, -1, 0
	s_nop 8
	v_cndmask_b32_e32 v97, v113, v231, vcc
	v_cndmask_b32_e32 v96, v112, v231, vcc
	v_max_f32_e32 v112, v97, v97
	v_max_f32_e32 v113, v96, v96
	v_cndmask_b32_e32 v99, v115, v231, vcc
	v_cndmask_b32_e32 v98, v114, v231, vcc
	v_max_f32_e32 v112, v113, v112
	v_cndmask_b32_e32 v101, v117, v231, vcc
	v_cndmask_b32_e32 v100, v116, v231, vcc
	v_max3_f32 v112, v112, v98, v99
	v_cndmask_b32_e32 v103, v119, v231, vcc
	v_cndmask_b32_e32 v102, v118, v231, vcc
	v_max3_f32 v112, v112, v100, v101
	v_cndmask_b32_e32 v105, v121, v231, vcc
	v_cndmask_b32_e32 v104, v120, v231, vcc
	v_max3_f32 v112, v112, v102, v103
	v_cndmask_b32_e32 v107, v123, v231, vcc
	v_cndmask_b32_e32 v106, v122, v231, vcc
	v_max3_f32 v112, v112, v104, v105
	v_cndmask_b32_e32 v109, v125, v231, vcc
	v_cndmask_b32_e32 v108, v124, v231, vcc
	v_max3_f32 v112, v112, v106, v107
	v_cndmask_b32_e32 v111, v127, v231, vcc
	v_cndmask_b32_e32 v110, v126, v231, vcc
	v_max3_f32 v112, v112, v108, v109
	v_cndmask_b32_e32 v81, v129, v231, vcc
	v_cndmask_b32_e32 v80, v128, v231, vcc
	v_max3_f32 v112, v112, v110, v111
	v_cndmask_b32_e32 v83, v131, v231, vcc
	v_cndmask_b32_e32 v82, v130, v231, vcc
	v_max3_f32 v112, v112, v80, v81
	v_cndmask_b32_e32 v85, v133, v231, vcc
	v_cndmask_b32_e32 v84, v132, v231, vcc
	v_max3_f32 v112, v112, v82, v83
	v_cndmask_b32_e32 v87, v135, v231, vcc
	v_cndmask_b32_e32 v86, v134, v231, vcc
	v_max3_f32 v112, v112, v84, v85
	v_cndmask_b32_e32 v89, v137, v231, vcc
	v_cndmask_b32_e32 v88, v136, v231, vcc
	v_max3_f32 v112, v112, v86, v87
	v_cndmask_b32_e32 v91, v139, v231, vcc
	v_cndmask_b32_e32 v90, v138, v231, vcc
	v_max3_f32 v112, v112, v88, v89
	v_lshl_add_u32 v0, s60, 14, v235
	ds_read_b64_tr_b16 v[208:209], v0 offset:0
	v_cndmask_b32_e32 v93, v141, v231, vcc
	v_cndmask_b32_e32 v92, v140, v231, vcc
	v_max3_f32 v112, v112, v90, v91
	ds_read_b64_tr_b16 v[210:211], v0 offset:0x800
	v_cndmask_b32_e32 v95, v143, v231, vcc
	v_cndmask_b32_e32 v94, v142, v231, vcc
	v_max3_f32 v112, v112, v92, v93
	ds_read_b64_tr_b16 v[204:205], v0 offset:0x1000
	v_max3_f32 v112, v112, v94, v95
	ds_read_b64_tr_b16 v[206:207], v0 offset:0x1800
	v_mov_b32_e32 v113, v112
	ds_read_b64_tr_b16 v[200:201], v0 offset:0x2000
	s_nop 1
	v_permlane32_swap_b32_e32 v112, v113
	ds_read_b64_tr_b16 v[202:203], v0 offset:0x2800
	v_max_f32_e32 v113, v113, v113
	v_max_f32_e32 v112, v112, v112
	ds_read_b64_tr_b16 v[196:197], v0 offset:0x3000
	v_max_f32_e32 v112, v112, v113
	ds_read_b64_tr_b16 v[198:199], v0 offset:0x3800
	v_sub_f32_e32 v113, v112, v236
	v_cmp_ge_f32_e32 vcc, s29, v113
	s_cmp_eq_u64 vcc, exec
	v_mov_b32_e32 v240, 1.0
	s_cbranch_scc0 .LBB0_883
.LBB0_872:
	ds_read_b64_tr_b16 v[112:113], v0 offset:0x200
	ds_read_b64_tr_b16 v[114:115], v0 offset:0xa00
	ds_read_b64_tr_b16 v[116:117], v0 offset:0x1200
	ds_read_b64_tr_b16 v[118:119], v0 offset:0x1a00
	ds_read_b64_tr_b16 v[120:121], v0 offset:0x2200
	ds_read_b64_tr_b16 v[122:123], v0 offset:0x2a00
	ds_read_b64_tr_b16 v[124:125], v0 offset:0x3200
	ds_read_b64_tr_b16 v[126:127], v0 offset:0x3a00
	s_waitcnt lgkmcnt(8)
	v_sub_f32_e32 v96, v96, v236
	v_mfma_f32_32x32x16_bf16 v[64:79], v[192:195], v[208:211], v[64:79]
	v_sub_f32_e32 v80, v80, v236
	v_exp_f32_e32 v96, v96
	v_exp_f32_e32 v80, v80
	v_mfma_f32_32x32x16_bf16 v[64:79], v[10:13], v[204:207], v[64:79]
	v_sub_f32_e32 v97, v97, v236
	v_sub_f32_e32 v81, v81, v236
	v_exp_f32_e32 v97, v97
	v_exp_f32_e32 v81, v81
	v_mfma_f32_32x32x16_bf16 v[64:79], v[6:9], v[200:203], v[64:79]
	v_sub_f32_e32 v98, v98, v236
	v_sub_f32_e32 v82, v82, v236
	v_exp_f32_e32 v98, v98
	v_exp_f32_e32 v82, v82
	v_mfma_f32_32x32x16_bf16 v[64:79], v[2:5], v[196:199], v[64:79]
	v_sub_f32_e32 v99, v99, v236
	v_sub_f32_e32 v83, v83, v236
	v_exp_f32_e32 v99, v99
	v_exp_f32_e32 v83, v83
	ds_read_b64_tr_b16 v[128:129], v0 offset:0x400
	ds_read_b64_tr_b16 v[130:131], v0 offset:0xc00
	ds_read_b64_tr_b16 v[132:133], v0 offset:0x1400
	ds_read_b64_tr_b16 v[134:135], v0 offset:0x1c00
	ds_read_b64_tr_b16 v[136:137], v0 offset:0x2400
	ds_read_b64_tr_b16 v[138:139], v0 offset:0x2c00
	ds_read_b64_tr_b16 v[140:141], v0 offset:0x3400
	ds_read_b64_tr_b16 v[142:143], v0 offset:0x3c00
	s_waitcnt lgkmcnt(8)
	s_nop 0
	v_sub_f32_e32 v100, v100, v236
	v_mfma_f32_32x32x16_bf16 v[48:63], v[192:195], v[112:115], v[48:63]
	v_sub_f32_e32 v84, v84, v236
	v_exp_f32_e32 v100, v100
	v_exp_f32_e32 v84, v84
	v_mfma_f32_32x32x16_bf16 v[48:63], v[10:13], v[116:119], v[48:63]
	v_sub_f32_e32 v101, v101, v236
	v_sub_f32_e32 v85, v85, v236
	v_exp_f32_e32 v101, v101
	v_exp_f32_e32 v85, v85
	v_mfma_f32_32x32x16_bf16 v[48:63], v[6:9], v[120:123], v[48:63]
	v_sub_f32_e32 v102, v102, v236
	v_sub_f32_e32 v86, v86, v236
	v_exp_f32_e32 v102, v102
	v_exp_f32_e32 v86, v86
	v_mfma_f32_32x32x16_bf16 v[48:63], v[2:5], v[124:127], v[48:63]
	v_sub_f32_e32 v103, v103, v236
	v_sub_f32_e32 v87, v87, v236
	v_exp_f32_e32 v103, v103
	v_exp_f32_e32 v87, v87
	ds_read_b64_tr_b16 v[112:113], v0 offset:0x600
	ds_read_b64_tr_b16 v[114:115], v0 offset:0xe00
	ds_read_b64_tr_b16 v[116:117], v0 offset:0x1600
	ds_read_b64_tr_b16 v[118:119], v0 offset:0x1e00
	ds_read_b64_tr_b16 v[120:121], v0 offset:0x2600
	ds_read_b64_tr_b16 v[122:123], v0 offset:0x2e00
	ds_read_b64_tr_b16 v[124:125], v0 offset:0x3600
	ds_read_b64_tr_b16 v[126:127], v0 offset:0x3e00
	s_waitcnt lgkmcnt(8)
	s_nop 0
	v_sub_f32_e32 v0, v104, v236
	v_mfma_f32_32x32x16_bf16 v[32:47], v[192:195], v[128:131], v[32:47]
	v_sub_f32_e32 v88, v88, v236
	v_exp_f32_e32 v104, v0
	v_exp_f32_e32 v88, v88
	v_mfma_f32_32x32x16_bf16 v[32:47], v[10:13], v[132:135], v[32:47]
	v_sub_f32_e32 v0, v105, v236
	v_sub_f32_e32 v89, v89, v236
	v_exp_f32_e32 v105, v0
	v_exp_f32_e32 v89, v89
	v_mfma_f32_32x32x16_bf16 v[32:47], v[6:9], v[136:139], v[32:47]
	v_sub_f32_e32 v0, v106, v236
	v_sub_f32_e32 v90, v90, v236
	v_exp_f32_e32 v106, v0
	v_exp_f32_e32 v90, v90
	v_mfma_f32_32x32x16_bf16 v[32:47], v[2:5], v[140:143], v[32:47]
	v_sub_f32_e32 v0, v107, v236
	v_sub_f32_e32 v91, v91, v236
	v_exp_f32_e32 v107, v0
	v_exp_f32_e32 v91, v91
	s_waitcnt lgkmcnt(0)
	s_nop 0
	v_sub_f32_e32 v0, v108, v236
	v_mfma_f32_32x32x16_bf16 v[16:31], v[192:195], v[112:115], v[16:31]
	v_sub_f32_e32 v92, v92, v236
	v_exp_f32_e32 v108, v0
	v_exp_f32_e32 v92, v92
	v_mfma_f32_32x32x16_bf16 v[16:31], v[10:13], v[116:119], v[16:31]
	v_sub_f32_e32 v0, v109, v236
	v_sub_f32_e32 v93, v93, v236
	v_exp_f32_e32 v109, v0
	v_exp_f32_e32 v93, v93
	v_mfma_f32_32x32x16_bf16 v[16:31], v[6:9], v[120:123], v[16:31]
	v_sub_f32_e32 v0, v110, v236
	v_sub_f32_e32 v10, v94, v236
	v_exp_f32_e32 v110, v0
	v_exp_f32_e32 v94, v10
	v_mfma_f32_32x32x16_bf16 v[16:31], v[2:5], v[124:127], v[16:31]
	v_sub_f32_e32 v0, v111, v236
	v_sub_f32_e32 v6, v95, v236
	v_exp_f32_e32 v111, v0
	v_exp_f32_e32 v95, v6
	v_cmp_gt_f32_e32 vcc, 1.0, v240
	s_cbranch_vccz .LBB0_876
.Lresc_mla_odd_blk:
	s_and_saveexec_b64 s[60:61], s[4:5]
	ds_write_b32 v233, v240 offset:128
	s_or_b64 exec, exec, s[60:61]
	s_waitcnt lgkmcnt(0)
	ds_read_b128 v[2:5], v232 offset:224
	ds_read_b128 v[6:9], v232 offset:192
	ds_read_b128 v[10:13], v232 offset:160
	ds_read_b128 v[112:115], v232 offset:128
	s_waitcnt lgkmcnt(0)
	v_pk_mul_f32 v[78:79], v[78:79], v[4:5]
	v_pk_mul_f32 v[74:75], v[74:75], v[8:9]
	v_pk_mul_f32 v[70:71], v[70:71], v[12:13]
	v_pk_mul_f32 v[66:67], v[66:67], v[114:115]
	v_pk_mul_f32 v[76:77], v[76:77], v[2:3]
	v_pk_mul_f32 v[72:73], v[72:73], v[6:7]
	v_pk_mul_f32 v[68:69], v[68:69], v[10:11]
	v_pk_mul_f32 v[64:65], v[64:65], v[112:113]
	v_pk_mul_f32 v[62:63], v[62:63], v[4:5]
	v_pk_mul_f32 v[58:59], v[58:59], v[8:9]
	v_pk_mul_f32 v[54:55], v[54:55], v[12:13]
	v_pk_mul_f32 v[50:51], v[50:51], v[114:115]
	v_pk_mul_f32 v[60:61], v[60:61], v[2:3]
	v_pk_mul_f32 v[56:57], v[56:57], v[6:7]
	v_pk_mul_f32 v[52:53], v[52:53], v[10:11]
	v_pk_mul_f32 v[48:49], v[48:49], v[112:113]
	v_pk_mul_f32 v[46:47], v[46:47], v[4:5]
	v_pk_mul_f32 v[42:43], v[42:43], v[8:9]
	v_pk_mul_f32 v[38:39], v[38:39], v[12:13]
	v_pk_mul_f32 v[34:35], v[34:35], v[114:115]
	v_pk_mul_f32 v[44:45], v[44:45], v[2:3]
	v_pk_mul_f32 v[40:41], v[40:41], v[6:7]
	v_pk_mul_f32 v[36:37], v[36:37], v[10:11]
	v_pk_mul_f32 v[32:33], v[32:33], v[112:113]
	v_pk_mul_f32 v[30:31], v[30:31], v[4:5]
	v_pk_mul_f32 v[26:27], v[26:27], v[8:9]
	v_pk_mul_f32 v[22:23], v[22:23], v[12:13]
	v_pk_mul_f32 v[18:19], v[18:19], v[114:115]
	v_pk_mul_f32 v[28:29], v[28:29], v[2:3]
	v_pk_mul_f32 v[24:25], v[24:25], v[6:7]
	v_pk_mul_f32 v[20:21], v[20:21], v[10:11]
	v_pk_mul_f32 v[16:17], v[16:17], v[112:113]
	s_branch .LBB0_876

.Lold_mla_even:
	s_cselect_b64 vcc, -1, 0
	s_nop 8
	v_cndmask_b32_e32 v97, v231, v113, vcc
	v_cndmask_b32_e32 v96, v231, v112, vcc
	v_max_f32_e32 v0, v97, v97
	v_max_f32_e32 v112, v96, v96
	v_cndmask_b32_e32 v99, v231, v115, vcc
	v_cndmask_b32_e32 v98, v231, v114, vcc
	v_max_f32_e32 v0, v112, v0
	v_cndmask_b32_e32 v101, v231, v117, vcc
	v_cndmask_b32_e32 v100, v231, v116, vcc
	v_max3_f32 v0, v0, v98, v99
	v_cndmask_b32_e32 v103, v231, v119, vcc
	v_cndmask_b32_e32 v102, v231, v118, vcc
	v_max3_f32 v0, v0, v100, v101
	v_cndmask_b32_e32 v105, v231, v121, vcc
	v_cndmask_b32_e32 v104, v231, v120, vcc
	v_max3_f32 v0, v0, v102, v103
	v_cndmask_b32_e32 v107, v231, v123, vcc
	v_cndmask_b32_e32 v106, v231, v122, vcc
	v_max3_f32 v0, v0, v104, v105
	v_cndmask_b32_e32 v109, v231, v125, vcc
	v_cndmask_b32_e32 v108, v231, v124, vcc
	v_max3_f32 v0, v0, v106, v107
	v_cndmask_b32_e32 v111, v231, v127, vcc
	v_cndmask_b32_e32 v110, v231, v126, vcc
	v_max3_f32 v0, v0, v108, v109
	v_cndmask_b32_e32 v81, v231, v129, vcc
	v_cndmask_b32_e32 v80, v231, v128, vcc
	v_max3_f32 v0, v0, v110, v111
	v_cndmask_b32_e32 v83, v231, v131, vcc
	v_cndmask_b32_e32 v82, v231, v130, vcc
	v_max3_f32 v0, v0, v80, v81
	v_cndmask_b32_e32 v85, v231, v133, vcc
	v_cndmask_b32_e32 v84, v231, v132, vcc
	v_max3_f32 v0, v0, v82, v83
	v_cndmask_b32_e32 v87, v231, v135, vcc
	v_cndmask_b32_e32 v86, v231, v134, vcc
	v_max3_f32 v0, v0, v84, v85
	v_cndmask_b32_e32 v89, v231, v137, vcc
	v_cndmask_b32_e32 v88, v231, v136, vcc
	v_max3_f32 v0, v0, v86, v87
	v_cndmask_b32_e32 v91, v231, v139, vcc
	v_cndmask_b32_e32 v90, v231, v138, vcc
	v_max3_f32 v0, v0, v88, v89
	v_lshl_add_u32 v243, s79, 14, v235
	ds_read_b64_tr_b16 v[208:209], v243 offset:0
	v_cndmask_b32_e32 v93, v231, v141, vcc
	v_cndmask_b32_e32 v92, v231, v140, vcc
	v_max3_f32 v0, v0, v90, v91
	ds_read_b64_tr_b16 v[210:211], v243 offset:0x800
	v_cndmask_b32_e32 v95, v231, v143, vcc
	v_cndmask_b32_e32 v94, v231, v142, vcc
	v_max3_f32 v0, v0, v92, v93
	ds_read_b64_tr_b16 v[204:205], v243 offset:0x1000
	v_max3_f32 v0, v0, v94, v95
	ds_read_b64_tr_b16 v[206:207], v243 offset:0x1800
	v_mov_b32_e32 v112, v0
	ds_read_b64_tr_b16 v[200:201], v243 offset:0x2000
	s_nop 1
	v_permlane32_swap_b32_e32 v0, v112
	ds_read_b64_tr_b16 v[202:203], v243 offset:0x2800
	v_max_f32_e32 v112, v112, v112
	v_max_f32_e32 v0, v0, v0
	ds_read_b64_tr_b16 v[196:197], v243 offset:0x3000
	v_max_f32_e32 v112, v0, v112
	ds_read_b64_tr_b16 v[198:199], v243 offset:0x3800
	v_sub_f32_e32 v0, v112, v236
	v_cmp_ge_f32_e32 vcc, s29, v0
	s_cmp_eq_u64 vcc, exec
	v_mov_b32_e32 v0, 1.0
	s_cbranch_scc0 .LBB0_884
.LBB0_877:
	ds_read_b64_tr_b16 v[112:113], v243 offset:0x200
	ds_read_b64_tr_b16 v[114:115], v243 offset:0xa00
	ds_read_b64_tr_b16 v[116:117], v243 offset:0x1200
	ds_read_b64_tr_b16 v[118:119], v243 offset:0x1a00
	ds_read_b64_tr_b16 v[120:121], v243 offset:0x2200
	ds_read_b64_tr_b16 v[122:123], v243 offset:0x2a00
	ds_read_b64_tr_b16 v[124:125], v243 offset:0x3200
	ds_read_b64_tr_b16 v[126:127], v243 offset:0x3a00
	s_waitcnt lgkmcnt(8)
	v_sub_f32_e32 v96, v96, v236
	v_mfma_f32_32x32x16_bf16 v[64:79], v[192:195], v[208:211], v[64:79]
	v_sub_f32_e32 v80, v80, v236
	v_exp_f32_e32 v96, v96
	v_exp_f32_e32 v80, v80
	v_mfma_f32_32x32x16_bf16 v[64:79], v[10:13], v[204:207], v[64:79]
	v_sub_f32_e32 v97, v97, v236
	v_sub_f32_e32 v81, v81, v236
	v_exp_f32_e32 v97, v97
	v_exp_f32_e32 v81, v81
	v_mfma_f32_32x32x16_bf16 v[64:79], v[6:9], v[200:203], v[64:79]
	v_sub_f32_e32 v98, v98, v236
	v_sub_f32_e32 v82, v82, v236
	v_exp_f32_e32 v98, v98
	v_exp_f32_e32 v82, v82
	v_mfma_f32_32x32x16_bf16 v[64:79], v[2:5], v[196:199], v[64:79]
	v_sub_f32_e32 v99, v99, v236
	v_sub_f32_e32 v83, v83, v236
	v_exp_f32_e32 v99, v99
	v_exp_f32_e32 v83, v83
	ds_read_b64_tr_b16 v[128:129], v243 offset:0x400
	ds_read_b64_tr_b16 v[130:131], v243 offset:0xc00
	ds_read_b64_tr_b16 v[132:133], v243 offset:0x1400
	ds_read_b64_tr_b16 v[134:135], v243 offset:0x1c00
	ds_read_b64_tr_b16 v[136:137], v243 offset:0x2400
	ds_read_b64_tr_b16 v[138:139], v243 offset:0x2c00
	ds_read_b64_tr_b16 v[140:141], v243 offset:0x3400
	ds_read_b64_tr_b16 v[142:143], v243 offset:0x3c00
	s_waitcnt lgkmcnt(8)
	s_nop 0
	v_sub_f32_e32 v100, v100, v236
	v_mfma_f32_32x32x16_bf16 v[48:63], v[192:195], v[112:115], v[48:63]
	v_sub_f32_e32 v84, v84, v236
	v_exp_f32_e32 v100, v100
	v_exp_f32_e32 v84, v84
	v_mfma_f32_32x32x16_bf16 v[48:63], v[10:13], v[116:119], v[48:63]
	v_sub_f32_e32 v101, v101, v236
	v_sub_f32_e32 v85, v85, v236
	v_exp_f32_e32 v101, v101
	v_exp_f32_e32 v85, v85
	v_mfma_f32_32x32x16_bf16 v[48:63], v[6:9], v[120:123], v[48:63]
	v_sub_f32_e32 v102, v102, v236
	v_sub_f32_e32 v86, v86, v236
	v_exp_f32_e32 v102, v102
	v_exp_f32_e32 v86, v86
	v_mfma_f32_32x32x16_bf16 v[48:63], v[2:5], v[124:127], v[48:63]
	v_sub_f32_e32 v103, v103, v236
	v_sub_f32_e32 v87, v87, v236
	v_exp_f32_e32 v103, v103
	v_exp_f32_e32 v87, v87
	ds_read_b64_tr_b16 v[112:113], v243 offset:0x600
	ds_read_b64_tr_b16 v[114:115], v243 offset:0xe00
	ds_read_b64_tr_b16 v[116:117], v243 offset:0x1600
	ds_read_b64_tr_b16 v[118:119], v243 offset:0x1e00
	ds_read_b64_tr_b16 v[120:121], v243 offset:0x2600
	ds_read_b64_tr_b16 v[122:123], v243 offset:0x2e00
	ds_read_b64_tr_b16 v[124:125], v243 offset:0x3600
	ds_read_b64_tr_b16 v[126:127], v243 offset:0x3e00
	s_waitcnt lgkmcnt(8)
	s_nop 0
	v_sub_f32_e32 v104, v104, v236
	v_mfma_f32_32x32x16_bf16 v[32:47], v[192:195], v[128:131], v[32:47]
	v_sub_f32_e32 v88, v88, v236
	v_exp_f32_e32 v104, v104
	v_exp_f32_e32 v88, v88
	v_mfma_f32_32x32x16_bf16 v[32:47], v[10:13], v[132:135], v[32:47]
	v_sub_f32_e32 v105, v105, v236
	v_sub_f32_e32 v89, v89, v236
	v_exp_f32_e32 v105, v105
	v_exp_f32_e32 v89, v89
	v_mfma_f32_32x32x16_bf16 v[32:47], v[6:9], v[136:139], v[32:47]
	v_sub_f32_e32 v106, v106, v236
	v_sub_f32_e32 v90, v90, v236
	v_exp_f32_e32 v106, v106
	v_exp_f32_e32 v90, v90
	v_mfma_f32_32x32x16_bf16 v[32:47], v[2:5], v[140:143], v[32:47]
	v_sub_f32_e32 v107, v107, v236
	v_sub_f32_e32 v91, v91, v236
	v_exp_f32_e32 v107, v107
	v_exp_f32_e32 v91, v91
	s_waitcnt lgkmcnt(0)
	s_nop 0
	v_sub_f32_e32 v108, v108, v236
	v_mfma_f32_32x32x16_bf16 v[16:31], v[192:195], v[112:115], v[16:31]
	v_sub_f32_e32 v92, v92, v236
	v_exp_f32_e32 v108, v108
	v_exp_f32_e32 v92, v92
	v_mfma_f32_32x32x16_bf16 v[16:31], v[10:13], v[116:119], v[16:31]
	v_sub_f32_e32 v109, v109, v236
	v_sub_f32_e32 v93, v93, v236
	v_exp_f32_e32 v109, v109
	v_exp_f32_e32 v93, v93
	v_mfma_f32_32x32x16_bf16 v[16:31], v[6:9], v[120:123], v[16:31]
	v_sub_f32_e32 v10, v110, v236
	v_sub_f32_e32 v11, v94, v236
	v_exp_f32_e32 v110, v10
	v_exp_f32_e32 v94, v11
	v_mfma_f32_32x32x16_bf16 v[16:31], v[2:5], v[124:127], v[16:31]
	v_sub_f32_e32 v6, v111, v236
	v_sub_f32_e32 v7, v95, v236
	v_exp_f32_e32 v111, v6
	v_exp_f32_e32 v95, v7
	v_cmp_gt_f32_e32 vcc, 1.0, v0
	s_cbranch_vccz .LBB0_881
.Lresc_mla_even_blk:
	s_and_saveexec_b64 s[60:61], s[4:5]
	ds_write_b32 v233, v0 offset:128
	s_or_b64 exec, exec, s[60:61]
	s_waitcnt lgkmcnt(0)
	ds_read_b128 v[2:5], v232 offset:224
	ds_read_b128 v[6:9], v232 offset:192
	ds_read_b128 v[10:13], v232 offset:160
	ds_read_b128 v[112:115], v232 offset:128
	s_waitcnt lgkmcnt(0)
	v_pk_mul_f32 v[78:79], v[78:79], v[4:5]
	v_pk_mul_f32 v[74:75], v[74:75], v[8:9]
	v_pk_mul_f32 v[70:71], v[70:71], v[12:13]
	v_pk_mul_f32 v[66:67], v[66:67], v[114:115]
	v_pk_mul_f32 v[76:77], v[76:77], v[2:3]
	v_pk_mul_f32 v[72:73], v[72:73], v[6:7]
	v_pk_mul_f32 v[68:69], v[68:69], v[10:11]
	v_pk_mul_f32 v[64:65], v[64:65], v[112:113]
	v_pk_mul_f32 v[62:63], v[62:63], v[4:5]
	v_pk_mul_f32 v[58:59], v[58:59], v[8:9]
	v_pk_mul_f32 v[54:55], v[54:55], v[12:13]
	v_pk_mul_f32 v[50:51], v[50:51], v[114:115]
	v_pk_mul_f32 v[60:61], v[60:61], v[2:3]
	v_pk_mul_f32 v[56:57], v[56:57], v[6:7]
	v_pk_mul_f32 v[52:53], v[52:53], v[10:11]
	v_pk_mul_f32 v[48:49], v[48:49], v[112:113]
	v_pk_mul_f32 v[46:47], v[46:47], v[4:5]
	v_pk_mul_f32 v[42:43], v[42:43], v[8:9]
	v_pk_mul_f32 v[38:39], v[38:39], v[12:13]
	v_pk_mul_f32 v[34:35], v[34:35], v[114:115]
	v_pk_mul_f32 v[44:45], v[44:45], v[2:3]
	v_pk_mul_f32 v[40:41], v[40:41], v[6:7]
	v_pk_mul_f32 v[36:37], v[36:37], v[10:11]
	v_pk_mul_f32 v[32:33], v[32:33], v[112:113]
	v_pk_mul_f32 v[30:31], v[30:31], v[4:5]
	v_pk_mul_f32 v[26:27], v[26:27], v[8:9]
	v_pk_mul_f32 v[22:23], v[22:23], v[12:13]
	v_pk_mul_f32 v[18:19], v[18:19], v[114:115]
	v_pk_mul_f32 v[28:29], v[28:29], v[2:3]
	v_pk_mul_f32 v[24:25], v[24:25], v[6:7]
	v_pk_mul_f32 v[20:21], v[20:21], v[10:11]
	v_pk_mul_f32 v[16:17], v[16:17], v[112:113]
	s_branch .LBB0_881

.LBB0_1422:
	s_lshl_b32 s18, s44, 14
	s_add_i32 s52, s81, s18
	s_mov_b32 m0, s52
	v_lshl_add_u64 v[0:1], v[194:195], 0, s[14:15]
	global_load_lds_dwordx4 v[194:195], off
	s_add_i32 m0, s52, 0x2000
	s_mul_i32 s52, s54, 0x2100
	s_add_i32 s52, s22, s52
	global_load_lds_dwordx4 v[0:1], off
	s_add_i32 m0, s52, 0xc000
	s_add_i32 s52, s45, -1
	s_cmp_lt_u32 s52, s2
	s_cselect_b32 s55, s52, s3
	s_lshl_b32 s56, s55, 6
	v_mad_u64_u32 v[0:1], s[52:53], s56, v209, v[192:193]
	v_lshl_add_u64 v[0:1], v[0:1], 0, s[10:11]
	global_load_lds_dwordx4 v[0:1], off
	s_mul_i32 s52, s55, 0x60000
	s_mul_hi_u32 s53, s56, 0x1800
	s_mul_i32 s55, s69, 0x2100
	s_add_i32 s71, s55, 0
	s_sub_i32 s55, s65, 64
	v_cvt_f32_u32_e32 v0, s55
	v_add_u32_e32 v166, s71, v220
	v_add_u32_e32 v167, s71, v217
	ds_read_b128 v[4:7], v166 offset:49152
	ds_read_b128 v[8:11], v167 offset:49152
	v_sub_f32_e32 v196, v0, v161
	v_fma_f32 v0, v210, v196, -v221
	v_cvt_pk_bf16_f32 v1, v0, v3
	v_lshlrev_b32_e32 v1, 16, v1
	v_sub_f32_e32 v0, v0, v1
	v_cvt_pk_bf16_f32 v2, v0, v3
	v_lshlrev_b32_e32 v2, 16, v2
	v_sub_f32_e32 v0, v0, v2
	v_cvt_pk_bf16_f32 v1, v1, v2
	v_cvt_pk_bf16_f32 v0, v0, v3
	s_nop 0
	v_cndmask_b32_e64 v2, 0, v0, s[4:5]
	v_cndmask_b32_e64 v0, 0, v160, s[4:5]
	v_cndmask_b32_e64 v1, 0, v1, s[4:5]
	s_nop 1
	v_mfma_f32_32x32x16_bf16 v[128:143], v[248:251], v[0:3], 0
	v_mfma_f32_32x32x16_bf16 v[112:127], v[252:255], v[0:3], 0
	v_add_f32_e32 v1, 0, v96
	v_add_f32_e32 v1, v97, v1
	v_add_f32_e32 v1, v98, v1
	v_add_f32_e32 v1, v99, v1
	v_add_f32_e32 v1, v100, v1
	v_add_f32_e32 v1, v101, v1
	v_add_f32_e32 v1, v102, v1
	s_waitcnt lgkmcnt(0)
	v_mfma_f32_32x32x16_bf16 v[128:143], v[8:11], v[156:159], v[128:143]
	v_add_f32_e32 v1, v103, v1
	v_add_f32_e32 v1, v104, v1
	v_add_f32_e32 v1, v105, v1
	v_add_f32_e32 v1, v106, v1
	v_add_f32_e32 v1, v107, v1
	v_add_f32_e32 v1, v108, v1
	v_add_f32_e32 v1, v109, v1
	v_mfma_f32_32x32x16_bf16 v[112:127], v[4:7], v[156:159], v[112:127]
	ds_read_b128 v[4:7], v166 offset:51264
	ds_read_b128 v[8:11], v167 offset:51264
	v_add_f32_e32 v1, v110, v1
	v_add_f32_e32 v1, v111, v1
	v_add_f32_e32 v1, v80, v1
	v_add_f32_e32 v1, v81, v1
	v_add_f32_e32 v1, v82, v1
	v_add_f32_e32 v1, v83, v1
	s_waitcnt lgkmcnt(0)
	v_mfma_f32_32x32x16_bf16 v[128:143], v[8:11], v[152:155], v[128:143]
	v_add_f32_e32 v1, v84, v1
	v_add_f32_e32 v1, v85, v1
	v_add_f32_e32 v1, v86, v1
	v_add_f32_e32 v1, v87, v1
	v_add_f32_e32 v1, v88, v1
	v_add_f32_e32 v1, v89, v1
	v_add_f32_e32 v1, v90, v1
	v_mfma_f32_32x32x16_bf16 v[112:127], v[4:7], v[152:155], v[112:127]
	ds_read_b128 v[4:7], v166 offset:53376
	ds_read_b128 v[8:11], v167 offset:53376
	v_add_f32_e32 v1, v91, v1
	v_add_f32_e32 v1, v92, v1
	v_add_f32_e32 v1, v93, v1
	v_add_f32_e32 v1, v94, v1
	v_add_f32_e32 v223, v95, v1
	v_mov_b32_e32 v224, v223
	s_waitcnt lgkmcnt(0)
	v_mfma_f32_32x32x16_bf16 v[128:143], v[8:11], v[148:151], v[128:143]
	v_permlane32_swap_b32_e32 v223, v224
	v_mfma_f32_32x32x16_bf16 v[112:127], v[4:7], v[148:151], v[112:127]
	ds_read_b128 v[4:7], v166 offset:55488
	ds_read_b128 v[8:11], v167 offset:55488
	v_cvt_pk_bf16_f32 v166, v96, v97
	v_cvt_pk_bf16_f32 v167, v98, v99
	v_cvt_pk_bf16_f32 v168, v100, v101
	v_cvt_pk_bf16_f32 v169, v102, v103
	v_cvt_pk_bf16_f32 v12, v104, v105
	v_cvt_pk_bf16_f32 v13, v106, v107
	s_waitcnt lgkmcnt(0)
	v_mfma_f32_32x32x16_bf16 v[128:143], v[8:11], v[144:147], v[128:143]
	v_cvt_pk_bf16_f32 v14, v108, v109
	v_cvt_pk_bf16_f32 v15, v110, v111
	v_cvt_pk_bf16_f32 v8, v80, v81
	v_cvt_pk_bf16_f32 v9, v82, v83
	v_cvt_pk_bf16_f32 v10, v84, v85
	v_cvt_pk_bf16_f32 v11, v86, v87
	v_mfma_f32_32x32x16_bf16 v[112:127], v[4:7], v[144:147], v[112:127]
	v_cvt_pk_bf16_f32 v4, v88, v89
	v_cvt_pk_bf16_f32 v5, v90, v91
	v_cvt_pk_bf16_f32 v6, v92, v93
	v_cvt_pk_bf16_f32 v7, v94, v95
	v_lshl_add_u32 v1, s54, 14, v215
	ds_read_b64_tr_b16 v[182:183], v1 offset:0
	ds_read_b64_tr_b16 v[184:185], v1 offset:0x800
	ds_read_b64_tr_b16 v[178:179], v1 offset:0x1000
	ds_read_b64_tr_b16 v[180:181], v1 offset:0x1800
	s_add_i32 s70, s45, -3
	s_add_i32 s54, s19, s45
	ds_read_b64_tr_b16 v[174:175], v1 offset:0x2000
	s_cmp_eq_u32 s54, 3
	ds_read_b64_tr_b16 v[176:177], v1 offset:0x2800
	s_cselect_b64 s[54:55], -1, 0
	ds_read_b64_tr_b16 v[170:171], v1 offset:0x3000
	v_cndmask_b32_e64 v2, 0, 1, s[54:55]
	ds_read_b64_tr_b16 v[172:173], v1 offset:0x3800
	s_cmp_lt_i32 s70, s31
	s_cbranch_scc0 .Lold_odd
	v_max3_f32 v245, v128, v129, v130
	v_max3_f32 v246, v112, v113, v114
	v_max3_f32 v245, v245, v131, v132
	v_max3_f32 v246, v246, v115, v116
	v_max3_f32 v245, v245, v133, v134
	v_max3_f32 v246, v246, v117, v118
	v_max3_f32 v245, v245, v135, v136
	v_max3_f32 v246, v246, v119, v120
	v_max3_f32 v245, v245, v137, v138
	v_max3_f32 v246, v246, v121, v122
	v_max3_f32 v245, v245, v139, v140
	v_max3_f32 v246, v246, v123, v124
	v_max3_f32 v245, v245, v141, v142
	v_max3_f32 v246, v246, v125, v126
	v_max_f32_e32 v245, v245, v143
	v_max_f32_e32 v246, v246, v127
	v_max_f32_e32 v245, v245, v246
	v_mov_b32_e32 v246, v245
	s_nop 1
	v_permlane32_swap_b32_e32 v245, v246
	v_max_f32_e32 v245, v245, v246
	v_cmp_ge_f32_e32 vcc, s68, v245
	s_cmp_eq_u64 vcc, exec
	v_mov_b32_e32 v225, 1.0
	s_cbranch_scc0 .Lf_odd_resc
.Lf_odd_exp:
	v_exp_f32_e32 v82, v114
	v_exp_f32_e32 v83, v115
	ds_read_b64_tr_b16 v[114:115], v1 offset:0x200
	v_exp_f32_e32 v84, v116
	v_exp_f32_e32 v85, v117
	ds_read_b64_tr_b16 v[116:117], v1 offset:0xa00
	v_exp_f32_e32 v86, v118
	v_exp_f32_e32 v87, v119
	ds_read_b64_tr_b16 v[118:119], v1 offset:0x1200
	v_exp_f32_e32 v88, v120
	v_exp_f32_e32 v89, v121
	ds_read_b64_tr_b16 v[120:121], v1 offset:0x1a00
	v_exp_f32_e32 v90, v122
	v_exp_f32_e32 v91, v123
	ds_read_b64_tr_b16 v[122:123], v1 offset:0x2200
	v_exp_f32_e32 v92, v124
	v_exp_f32_e32 v93, v125
	ds_read_b64_tr_b16 v[124:125], v1 offset:0x2a00
	v_exp_f32_e32 v98, v130
	v_exp_f32_e32 v99, v131
	ds_read_b64_tr_b16 v[130:131], v1 offset:0x3200
	v_exp_f32_e32 v100, v132
	v_exp_f32_e32 v101, v133
	ds_read_b64_tr_b16 v[132:133], v1 offset:0x3a00
	s_waitcnt lgkmcnt(8)
	v_mfma_f32_32x32x16_bf16 v[64:79], v[166:169], v[182:185], v[64:79]
	v_exp_f32_e32 v94, v126
	v_exp_f32_e32 v95, v127
	v_exp_f32_e32 v96, v128
	v_mfma_f32_32x32x16_bf16 v[64:79], v[12:15], v[178:181], v[64:79]
	v_exp_f32_e32 v97, v129
	v_exp_f32_e32 v102, v134
	v_exp_f32_e32 v103, v135
	v_mfma_f32_32x32x16_bf16 v[64:79], v[8:11], v[174:177], v[64:79]
	v_exp_f32_e32 v104, v136
	v_exp_f32_e32 v105, v137
	v_exp_f32_e32 v106, v138
	v_mfma_f32_32x32x16_bf16 v[64:79], v[4:7], v[170:173], v[64:79]
	v_exp_f32_e32 v107, v139
	v_exp_f32_e32 v108, v140
	v_exp_f32_e32 v109, v141
	ds_read_b64_tr_b16 v[126:127], v1 offset:0x400
	ds_read_b64_tr_b16 v[128:129], v1 offset:0xc00
	ds_read_b64_tr_b16 v[134:135], v1 offset:0x1400
	ds_read_b64_tr_b16 v[136:137], v1 offset:0x1c00
	ds_read_b64_tr_b16 v[138:139], v1 offset:0x2400
	ds_read_b64_tr_b16 v[140:141], v1 offset:0x2c00
	ds_read_b64_tr_b16 v[170:171], v1 offset:0x3400
	ds_read_b64_tr_b16 v[172:173], v1 offset:0x3c00
	s_waitcnt lgkmcnt(8)
	v_mfma_f32_32x32x16_bf16 v[48:63], v[166:169], v[114:117], v[48:63]
	v_exp_f32_e32 v80, v112
	v_mfma_f32_32x32x16_bf16 v[48:63], v[12:15], v[118:121], v[48:63]
	v_exp_f32_e32 v81, v113
	v_mfma_f32_32x32x16_bf16 v[48:63], v[8:11], v[122:125], v[48:63]
	v_exp_f32_e32 v110, v142
	v_mfma_f32_32x32x16_bf16 v[48:63], v[4:7], v[130:133], v[48:63]
	v_exp_f32_e32 v111, v143
	ds_read_b64_tr_b16 v[112:113], v1 offset:0x600
	ds_read_b64_tr_b16 v[114:115], v1 offset:0xe00
	ds_read_b64_tr_b16 v[116:117], v1 offset:0x1600
	ds_read_b64_tr_b16 v[118:119], v1 offset:0x1e00
	ds_read_b64_tr_b16 v[120:121], v1 offset:0x2600
	ds_read_b64_tr_b16 v[122:123], v1 offset:0x2e00
	ds_read_b64_tr_b16 v[130:131], v1 offset:0x3600
	ds_read_b64_tr_b16 v[132:133], v1 offset:0x3e00
	s_waitcnt lgkmcnt(8)
	v_mfma_f32_32x32x16_bf16 v[32:47], v[166:169], v[126:129], v[32:47]
	v_mfma_f32_32x32x16_bf16 v[32:47], v[12:15], v[134:137], v[32:47]
	v_mfma_f32_32x32x16_bf16 v[32:47], v[8:11], v[138:141], v[32:47]
	v_mfma_f32_32x32x16_bf16 v[32:47], v[4:7], v[170:173], v[32:47]
	s_waitcnt lgkmcnt(0)
	v_mfma_f32_32x32x16_bf16 v[16:31], v[166:169], v[112:115], v[16:31]
	v_mfma_f32_32x32x16_bf16 v[16:31], v[12:15], v[116:119], v[16:31]
	v_mfma_f32_32x32x16_bf16 v[16:31], v[8:11], v[120:123], v[16:31]
	v_mfma_f32_32x32x16_bf16 v[16:31], v[4:7], v[130:133], v[16:31]
	v_cmp_gt_f32_e32 vcc, 1.0, v225
	s_cbranch_vccnz .Lresc_odd_blk
.LBB0_1437:
	s_waitcnt vmcnt(0)
	s_add_i32 s54, s44, 1
	s_cmp_lg_u32 s44, 2
	s_cselect_b32 s67, s54, 0
	s_waitcnt vmcnt(0)
	s_barrier
	s_lshl_b32 s66, s67, 14
	s_add_i32 s54, s81, s66
	v_lshl_add_u64 v[4:5], v[190:191], 0, s[52:53]
	s_mov_b32 m0, s54
	s_add_i32 s52, s71, s82
	global_load_lds_dwordx4 v[4:5], off
	v_lshl_add_u64 v[4:5], v[4:5], 0, s[14:15]
	s_add_i32 m0, s54, 0x2000
	s_add_i32 s52, s52, s27
	global_load_lds_dwordx4 v[4:5], off
	s_add_i32 m0, s52, 0xc000
	s_cmp_ge_u32 s45, s2
	s_cselect_b64 s[52:53], -1, 0
	s_cmp_lt_u32 s45, s2
	s_cselect_b32 s54, s45, s3
	s_lshl_b32 s54, s54, 6
	v_mad_u64_u32 v[4:5], s[54:55], s54, v209, v[192:193]
	v_lshl_add_u64 v[4:5], v[4:5], 0, s[10:11]
	global_load_lds_dwordx4 v[4:5], off
	v_cvt_f32_u32_e32 v1, s65
	s_mul_i32 s54, s44, 0x2100
	s_add_i32 s54, s54, 0
	v_add_u32_e32 v166, s54, v220
	v_sub_f32_e32 v196, v1, v161
	v_add_u32_e32 v167, s54, v217
	v_fma_f32 v1, v210, v196, -v221
	ds_read_b128 v[4:7], v166 offset:49152
	ds_read_b128 v[8:11], v167 offset:49152
	v_cvt_pk_bf16_f32 v2, v1, v3
	v_lshlrev_b32_e32 v2, 16, v2
	v_sub_f32_e32 v1, v1, v2
	v_cvt_pk_bf16_f32 v12, v1, v3
	v_lshlrev_b32_e32 v12, 16, v12
	v_sub_f32_e32 v1, v1, v12
	v_cvt_pk_bf16_f32 v12, v2, v12
	v_cvt_pk_bf16_f32 v1, v1, v3
	s_nop 0
	v_cndmask_b32_e64 v2, 0, v1, s[4:5]
	v_cndmask_b32_e64 v1, 0, v12, s[4:5]
	s_nop 1
	v_mfma_f32_32x32x16_bf16 v[128:143], v[248:251], v[0:3], 0
	s_nop 0
	v_mfma_f32_32x32x16_bf16 v[112:127], v[252:255], v[0:3], 0
	v_add_f32_e32 v1, 0, v96
	v_add_f32_e32 v1, v97, v1
	v_add_f32_e32 v1, v98, v1
	v_add_f32_e32 v1, v99, v1
	v_add_f32_e32 v1, v100, v1
	v_add_f32_e32 v1, v101, v1
	v_add_f32_e32 v1, v102, v1
	s_waitcnt lgkmcnt(0)
	v_mfma_f32_32x32x16_bf16 v[128:143], v[8:11], v[156:159], v[128:143]
	v_add_f32_e32 v1, v103, v1
	v_add_f32_e32 v1, v104, v1
	v_add_f32_e32 v1, v105, v1
	v_add_f32_e32 v1, v106, v1
	v_add_f32_e32 v1, v107, v1
	v_add_f32_e32 v1, v108, v1
	v_add_f32_e32 v1, v109, v1
	v_mfma_f32_32x32x16_bf16 v[112:127], v[4:7], v[156:159], v[112:127]
	ds_read_b128 v[4:7], v166 offset:51264
	ds_read_b128 v[8:11], v167 offset:51264
	v_add_f32_e32 v1, v110, v1
	v_add_f32_e32 v1, v111, v1
	v_add_f32_e32 v1, v80, v1
	v_add_f32_e32 v1, v81, v1
	v_add_f32_e32 v1, v82, v1
	v_add_f32_e32 v1, v83, v1
	s_waitcnt lgkmcnt(0)
	v_mfma_f32_32x32x16_bf16 v[128:143], v[8:11], v[152:155], v[128:143]
	v_add_f32_e32 v1, v84, v1
	v_add_f32_e32 v1, v85, v1
	v_add_f32_e32 v1, v86, v1
	v_add_f32_e32 v1, v87, v1
	v_add_f32_e32 v1, v88, v1
	v_add_f32_e32 v1, v89, v1
	v_add_f32_e32 v1, v90, v1
	v_mfma_f32_32x32x16_bf16 v[112:127], v[4:7], v[152:155], v[112:127]
	ds_read_b128 v[4:7], v166 offset:53376
	ds_read_b128 v[8:11], v167 offset:53376
	v_add_f32_e32 v1, v91, v1
	v_add_f32_e32 v1, v92, v1
	v_add_f32_e32 v1, v93, v1
	v_add_f32_e32 v1, v94, v1
	v_add_f32_e32 v1, v95, v1
	v_mov_b32_e32 v2, v1
	s_waitcnt lgkmcnt(0)
	v_mfma_f32_32x32x16_bf16 v[128:143], v[8:11], v[148:151], v[128:143]
	v_permlane32_swap_b32_e32 v1, v2
	v_mfma_f32_32x32x16_bf16 v[112:127], v[4:7], v[148:151], v[112:127]
	ds_read_b128 v[4:7], v166 offset:55488
	ds_read_b128 v[8:11], v167 offset:55488
	v_cvt_pk_bf16_f32 v166, v96, v97
	v_cvt_pk_bf16_f32 v167, v98, v99
	v_cvt_pk_bf16_f32 v168, v100, v101
	v_cvt_pk_bf16_f32 v169, v102, v103
	v_cvt_pk_bf16_f32 v12, v104, v105
	v_cvt_pk_bf16_f32 v13, v106, v107
	s_waitcnt lgkmcnt(0)
	v_mfma_f32_32x32x16_bf16 v[128:143], v[8:11], v[144:147], v[128:143]
	v_cvt_pk_bf16_f32 v14, v108, v109
	v_cvt_pk_bf16_f32 v15, v110, v111
	v_cvt_pk_bf16_f32 v8, v80, v81
	v_cvt_pk_bf16_f32 v9, v82, v83
	v_cvt_pk_bf16_f32 v10, v84, v85
	v_cvt_pk_bf16_f32 v11, v86, v87
	v_mfma_f32_32x32x16_bf16 v[112:127], v[4:7], v[144:147], v[112:127]
	v_cvt_pk_bf16_f32 v4, v88, v89
	v_cvt_pk_bf16_f32 v5, v90, v91
	v_cvt_pk_bf16_f32 v6, v92, v93
	v_cvt_pk_bf16_f32 v7, v94, v95
	v_lshl_add_u32 v162, s69, 14, v215
	ds_read_b64_tr_b16 v[182:183], v162 offset:0
	ds_read_b64_tr_b16 v[184:185], v162 offset:0x800
	ds_read_b64_tr_b16 v[178:179], v162 offset:0x1000
	ds_read_b64_tr_b16 v[180:181], v162 offset:0x1800
	s_add_i32 s54, s64, s45
	ds_read_b64_tr_b16 v[174:175], v162 offset:0x2000
	s_cmp_eq_u32 s54, 4
	ds_read_b64_tr_b16 v[176:177], v162 offset:0x2800
	s_cselect_b64 s[54:55], -1, 0
	ds_read_b64_tr_b16 v[170:171], v162 offset:0x3000
	v_cndmask_b32_e64 v80, 0, 1, s[54:55]
	ds_read_b64_tr_b16 v[172:173], v162 offset:0x3800
	s_add_i32 s98, s70, 2
	s_cmp_le_i32 s98, s31
	s_cbranch_scc0 .Lold_even
	v_max3_f32 v245, v128, v129, v130
	v_max3_f32 v246, v112, v113, v114
	v_max3_f32 v245, v245, v131, v132
	v_max3_f32 v246, v246, v115, v116
	v_max3_f32 v245, v245, v133, v134
	v_max3_f32 v246, v246, v117, v118
	v_max3_f32 v245, v245, v135, v136
	v_max3_f32 v246, v246, v119, v120
	v_max3_f32 v245, v245, v137, v138
	v_max3_f32 v246, v246, v121, v122
	v_max3_f32 v245, v245, v139, v140
	v_max3_f32 v246, v246, v123, v124
	v_max3_f32 v245, v245, v141, v142
	v_max3_f32 v246, v246, v125, v126
	v_max_f32_e32 v245, v245, v143
	v_max_f32_e32 v246, v246, v127
	v_max_f32_e32 v245, v245, v246
	v_mov_b32_e32 v246, v245
	s_nop 1
	v_permlane32_swap_b32_e32 v245, v246
	v_max_f32_e32 v245, v245, v246
	v_cmp_ge_f32_e32 vcc, s68, v245
	s_cmp_eq_u64 vcc, exec
	v_mov_b32_e32 v196, 1.0
	s_cbranch_scc0 .Lf_even_resc
.Lf_even_exp:
	v_exp_f32_e32 v82, v114
	v_exp_f32_e32 v83, v115
	ds_read_b64_tr_b16 v[114:115], v162 offset:0x200
	v_exp_f32_e32 v84, v116
	v_exp_f32_e32 v85, v117
	ds_read_b64_tr_b16 v[116:117], v162 offset:0xa00
	v_exp_f32_e32 v86, v118
	v_exp_f32_e32 v87, v119
	ds_read_b64_tr_b16 v[118:119], v162 offset:0x1200
	v_exp_f32_e32 v88, v120
	v_exp_f32_e32 v89, v121
	ds_read_b64_tr_b16 v[120:121], v162 offset:0x1a00
	v_exp_f32_e32 v90, v122
	v_exp_f32_e32 v91, v123
	ds_read_b64_tr_b16 v[122:123], v162 offset:0x2200
	v_exp_f32_e32 v92, v124
	v_exp_f32_e32 v93, v125
	ds_read_b64_tr_b16 v[124:125], v162 offset:0x2a00
	v_exp_f32_e32 v98, v130
	v_exp_f32_e32 v99, v131
	ds_read_b64_tr_b16 v[130:131], v162 offset:0x3200
	v_exp_f32_e32 v100, v132
	v_exp_f32_e32 v101, v133
	ds_read_b64_tr_b16 v[132:133], v162 offset:0x3a00
	s_waitcnt lgkmcnt(8)
	v_mfma_f32_32x32x16_bf16 v[64:79], v[166:169], v[182:185], v[64:79]
	v_exp_f32_e32 v94, v126
	v_exp_f32_e32 v95, v127
	v_exp_f32_e32 v96, v128
	v_mfma_f32_32x32x16_bf16 v[64:79], v[12:15], v[178:181], v[64:79]
	v_exp_f32_e32 v97, v129
	v_exp_f32_e32 v102, v134
	v_exp_f32_e32 v103, v135
	v_mfma_f32_32x32x16_bf16 v[64:79], v[8:11], v[174:177], v[64:79]
	v_exp_f32_e32 v104, v136
	v_exp_f32_e32 v105, v137
	v_exp_f32_e32 v106, v138
	v_mfma_f32_32x32x16_bf16 v[64:79], v[4:7], v[170:173], v[64:79]
	v_exp_f32_e32 v107, v139
	v_exp_f32_e32 v108, v140
	v_exp_f32_e32 v109, v141
	ds_read_b64_tr_b16 v[126:127], v162 offset:0x400
	ds_read_b64_tr_b16 v[128:129], v162 offset:0xc00
	ds_read_b64_tr_b16 v[134:135], v162 offset:0x1400
	ds_read_b64_tr_b16 v[136:137], v162 offset:0x1c00
	ds_read_b64_tr_b16 v[138:139], v162 offset:0x2400
	ds_read_b64_tr_b16 v[140:141], v162 offset:0x2c00
	ds_read_b64_tr_b16 v[170:171], v162 offset:0x3400
	ds_read_b64_tr_b16 v[172:173], v162 offset:0x3c00
	s_waitcnt lgkmcnt(8)
	v_mfma_f32_32x32x16_bf16 v[48:63], v[166:169], v[114:117], v[48:63]
	v_exp_f32_e32 v80, v112
	v_mfma_f32_32x32x16_bf16 v[48:63], v[12:15], v[118:121], v[48:63]
	v_exp_f32_e32 v81, v113
	v_mfma_f32_32x32x16_bf16 v[48:63], v[8:11], v[122:125], v[48:63]
	v_exp_f32_e32 v110, v142
	v_mfma_f32_32x32x16_bf16 v[48:63], v[4:7], v[130:133], v[48:63]
	v_exp_f32_e32 v111, v143
	ds_read_b64_tr_b16 v[112:113], v162 offset:0x600
	ds_read_b64_tr_b16 v[114:115], v162 offset:0xe00
	ds_read_b64_tr_b16 v[116:117], v162 offset:0x1600
	ds_read_b64_tr_b16 v[118:119], v162 offset:0x1e00
	ds_read_b64_tr_b16 v[120:121], v162 offset:0x2600
	ds_read_b64_tr_b16 v[122:123], v162 offset:0x2e00
	ds_read_b64_tr_b16 v[130:131], v162 offset:0x3600
	ds_read_b64_tr_b16 v[132:133], v162 offset:0x3e00
	s_waitcnt lgkmcnt(8)
	v_mfma_f32_32x32x16_bf16 v[32:47], v[166:169], v[126:129], v[32:47]
	v_mfma_f32_32x32x16_bf16 v[32:47], v[12:15], v[134:137], v[32:47]
	v_mfma_f32_32x32x16_bf16 v[32:47], v[8:11], v[138:141], v[32:47]
	v_mfma_f32_32x32x16_bf16 v[32:47], v[4:7], v[170:173], v[32:47]
	s_waitcnt lgkmcnt(0)
	v_mfma_f32_32x32x16_bf16 v[16:31], v[166:169], v[112:115], v[16:31]
	v_mfma_f32_32x32x16_bf16 v[16:31], v[12:15], v[116:119], v[16:31]
	v_mfma_f32_32x32x16_bf16 v[16:31], v[8:11], v[120:123], v[16:31]
	v_mfma_f32_32x32x16_bf16 v[16:31], v[4:7], v[130:133], v[16:31]
	v_cmp_gt_f32_e32 vcc, 1.0, v196
	s_cbranch_vccnz .Lresc_even_blk

.Lold_odd:
	s_cmp_le_i32 s70, s31
	v_readfirstlane_b32 s54, v2
	s_cselect_b32 s66, s54, 2
	s_cmp_gt_i32 s66, 1
	s_cbranch_scc0 .LBB0_1425
	s_mov_b64 s[54:55], -1
	v_mov_b32_e32 v197, 0xf149f2ca
	s_cbranch_execz .LBB0_1426
	v_mov_b32_e32 v142, 0xf149f2ca
	v_mov_b32_e32 v141, 0xf149f2ca
	v_mov_b32_e32 v140, 0xf149f2ca
	v_mov_b32_e32 v139, 0xf149f2ca
	v_mov_b32_e32 v138, 0xf149f2ca
	v_mov_b32_e32 v137, 0xf149f2ca
	v_mov_b32_e32 v136, 0xf149f2ca
	v_mov_b32_e32 v135, 0xf149f2ca
	v_mov_b32_e32 v134, 0xf149f2ca
	v_mov_b32_e32 v133, 0xf149f2ca
	v_mov_b32_e32 v132, 0xf149f2ca
	v_mov_b32_e32 v131, 0xf149f2ca
	v_mov_b32_e32 v130, 0xf149f2ca
	v_mov_b32_e32 v129, 0xf149f2ca
	v_mov_b32_e32 v128, 0xf149f2ca
	v_mov_b32_e32 v127, 0xf149f2ca
	v_mov_b32_e32 v126, 0xf149f2ca
	v_mov_b32_e32 v125, 0xf149f2ca
	v_mov_b32_e32 v124, 0xf149f2ca
	v_mov_b32_e32 v123, 0xf149f2ca
	v_mov_b32_e32 v122, 0xf149f2ca
	v_mov_b32_e32 v121, 0xf149f2ca
	v_mov_b32_e32 v120, 0xf149f2ca
	v_mov_b32_e32 v119, 0xf149f2ca
	v_mov_b32_e32 v118, 0xf149f2ca
	v_mov_b32_e32 v117, 0xf149f2ca
	v_mov_b32_e32 v116, 0xf149f2ca
	v_mov_b32_e32 v115, 0xf149f2ca
	v_mov_b32_e32 v114, 0xf149f2ca
	v_mov_b32_e32 v113, 0xf149f2ca
	v_mov_b32_e32 v112, 0xf149f2ca
	s_and_b64 vcc, exec, s[54:55]
	s_cbranch_vccnz .LBB0_1429
	s_branch .LBB0_1430

.LBB0_1433:
	ds_read_b64_tr_b16 v[114:115], v1 offset:0x200
	ds_read_b64_tr_b16 v[116:117], v1 offset:0xa00
	ds_read_b64_tr_b16 v[118:119], v1 offset:0x1200
	ds_read_b64_tr_b16 v[120:121], v1 offset:0x1a00
	ds_read_b64_tr_b16 v[122:123], v1 offset:0x2200
	ds_read_b64_tr_b16 v[124:125], v1 offset:0x2a00
	ds_read_b64_tr_b16 v[130:131], v1 offset:0x3200
	ds_read_b64_tr_b16 v[132:133], v1 offset:0x3a00
	s_waitcnt lgkmcnt(8)
	v_exp_f32_e32 v96, v128
	v_mfma_f32_32x32x16_bf16 v[64:79], v[166:169], v[182:185], v[64:79]
	v_exp_f32_e32 v80, v112
	v_mfma_f32_32x32x16_bf16 v[64:79], v[12:15], v[178:181], v[64:79]
	v_exp_f32_e32 v97, v97
	v_exp_f32_e32 v81, v81
	v_mfma_f32_32x32x16_bf16 v[64:79], v[8:11], v[174:177], v[64:79]
	v_exp_f32_e32 v98, v98
	v_exp_f32_e32 v82, v82
	v_mfma_f32_32x32x16_bf16 v[64:79], v[4:7], v[170:173], v[64:79]
	v_exp_f32_e32 v99, v99
	v_exp_f32_e32 v83, v83
	ds_read_b64_tr_b16 v[126:127], v1 offset:0x400
	ds_read_b64_tr_b16 v[128:129], v1 offset:0xc00
	ds_read_b64_tr_b16 v[134:135], v1 offset:0x1400
	ds_read_b64_tr_b16 v[136:137], v1 offset:0x1c00
	ds_read_b64_tr_b16 v[138:139], v1 offset:0x2400
	ds_read_b64_tr_b16 v[140:141], v1 offset:0x2c00
	ds_read_b64_tr_b16 v[170:171], v1 offset:0x3400
	ds_read_b64_tr_b16 v[172:173], v1 offset:0x3c00
	s_waitcnt lgkmcnt(8)
	s_nop 0
	v_exp_f32_e32 v100, v100
	v_mfma_f32_32x32x16_bf16 v[48:63], v[166:169], v[114:117], v[48:63]
	v_exp_f32_e32 v84, v84
	v_mfma_f32_32x32x16_bf16 v[48:63], v[12:15], v[118:121], v[48:63]
	v_exp_f32_e32 v101, v101
	v_exp_f32_e32 v85, v85
	v_mfma_f32_32x32x16_bf16 v[48:63], v[8:11], v[122:125], v[48:63]
	v_exp_f32_e32 v102, v102
	v_exp_f32_e32 v86, v86
	v_mfma_f32_32x32x16_bf16 v[48:63], v[4:7], v[130:133], v[48:63]
	v_exp_f32_e32 v103, v103
	v_exp_f32_e32 v87, v87
	ds_read_b64_tr_b16 v[112:113], v1 offset:0x600
	ds_read_b64_tr_b16 v[114:115], v1 offset:0xe00
	ds_read_b64_tr_b16 v[116:117], v1 offset:0x1600
	ds_read_b64_tr_b16 v[118:119], v1 offset:0x1e00
	ds_read_b64_tr_b16 v[120:121], v1 offset:0x2600
	ds_read_b64_tr_b16 v[122:123], v1 offset:0x2e00
	ds_read_b64_tr_b16 v[130:131], v1 offset:0x3600
	ds_read_b64_tr_b16 v[132:133], v1 offset:0x3e00
	s_waitcnt lgkmcnt(8)
	s_nop 0
	v_exp_f32_e32 v104, v104
	v_mfma_f32_32x32x16_bf16 v[32:47], v[166:169], v[126:129], v[32:47]
	v_exp_f32_e32 v88, v88
	v_mfma_f32_32x32x16_bf16 v[32:47], v[12:15], v[134:137], v[32:47]
	v_exp_f32_e32 v105, v105
	v_exp_f32_e32 v89, v89
	v_mfma_f32_32x32x16_bf16 v[32:47], v[8:11], v[138:141], v[32:47]
	v_exp_f32_e32 v106, v106
	v_exp_f32_e32 v90, v90
	v_mfma_f32_32x32x16_bf16 v[32:47], v[4:7], v[170:173], v[32:47]
	v_exp_f32_e32 v107, v107
	v_exp_f32_e32 v91, v91
	s_waitcnt lgkmcnt(0)
	s_nop 0
	v_exp_f32_e32 v108, v108
	v_mfma_f32_32x32x16_bf16 v[16:31], v[166:169], v[112:115], v[16:31]
	v_exp_f32_e32 v92, v92
	v_mfma_f32_32x32x16_bf16 v[16:31], v[12:15], v[116:119], v[16:31]
	v_exp_f32_e32 v109, v109
	v_exp_f32_e32 v93, v93
	v_mfma_f32_32x32x16_bf16 v[16:31], v[8:11], v[120:123], v[16:31]
	v_exp_f32_e32 v110, v110
	v_exp_f32_e32 v94, v94
	v_mfma_f32_32x32x16_bf16 v[16:31], v[4:7], v[130:133], v[16:31]
	v_exp_f32_e32 v111, v111
	v_exp_f32_e32 v95, v95
	v_cmp_gt_f32_e32 vcc, 1.0, v225
	s_cbranch_vccz .LBB0_1437
.Lresc_odd_blk:
	s_and_saveexec_b64 s[54:55], s[4:5]
	ds_write_b32 v213, v225 offset:128
	s_or_b64 exec, exec, s[54:55]
	s_waitcnt lgkmcnt(0)
	ds_read_b128 v[4:7], v212 offset:224
	ds_read_b128 v[8:11], v212 offset:192
	ds_read_b128 v[12:15], v212 offset:160
	ds_read_b128 v[112:115], v212 offset:128
	s_waitcnt lgkmcnt(0)
	v_pk_mul_f32 v[78:79], v[78:79], v[6:7]
	v_pk_mul_f32 v[74:75], v[74:75], v[10:11]
	v_pk_mul_f32 v[70:71], v[70:71], v[14:15]
	v_pk_mul_f32 v[66:67], v[66:67], v[114:115]
	v_pk_mul_f32 v[76:77], v[76:77], v[4:5]
	v_pk_mul_f32 v[72:73], v[72:73], v[8:9]
	v_pk_mul_f32 v[68:69], v[68:69], v[12:13]
	v_pk_mul_f32 v[64:65], v[64:65], v[112:113]
	v_pk_mul_f32 v[62:63], v[6:7], v[62:63]
	v_pk_mul_f32 v[58:59], v[10:11], v[58:59]
	v_pk_mul_f32 v[54:55], v[14:15], v[54:55]
	v_pk_mul_f32 v[50:51], v[114:115], v[50:51]
	v_pk_mul_f32 v[60:61], v[4:5], v[60:61]
	v_pk_mul_f32 v[56:57], v[8:9], v[56:57]
	v_pk_mul_f32 v[52:53], v[12:13], v[52:53]
	v_pk_mul_f32 v[48:49], v[112:113], v[48:49]
	v_pk_mul_f32 v[46:47], v[6:7], v[46:47]
	v_pk_mul_f32 v[42:43], v[10:11], v[42:43]
	v_pk_mul_f32 v[38:39], v[14:15], v[38:39]
	v_pk_mul_f32 v[34:35], v[114:115], v[34:35]
	v_pk_mul_f32 v[44:45], v[4:5], v[44:45]
	v_pk_mul_f32 v[40:41], v[8:9], v[40:41]
	v_pk_mul_f32 v[36:37], v[12:13], v[36:37]
	v_pk_mul_f32 v[32:33], v[112:113], v[32:33]
	v_pk_mul_f32 v[30:31], v[6:7], v[30:31]
	v_pk_mul_f32 v[26:27], v[10:11], v[26:27]
	v_pk_mul_f32 v[22:23], v[14:15], v[22:23]
	v_pk_mul_f32 v[18:19], v[114:115], v[18:19]
	v_pk_mul_f32 v[28:29], v[4:5], v[28:29]
	v_pk_mul_f32 v[24:25], v[8:9], v[24:25]
	v_pk_mul_f32 v[20:21], v[12:13], v[20:21]
	v_pk_mul_f32 v[16:17], v[112:113], v[16:17]
	s_branch .LBB0_1437

.Lold_even:
	s_cmp_lt_i32 s70, s31
	v_readfirstlane_b32 s54, v80
	s_cselect_b32 s69, s54, 2
	s_cmp_gt_i32 s69, 1
	s_cbranch_scc0 .LBB0_1440
	s_mov_b64 s[54:55], -1
	v_mov_b32_e32 v197, 0xf149f2ca
	s_cbranch_execz .LBB0_1441
	v_mov_b32_e32 v142, 0xf149f2ca
	v_mov_b32_e32 v141, 0xf149f2ca
	v_mov_b32_e32 v140, 0xf149f2ca
	v_mov_b32_e32 v139, 0xf149f2ca
	v_mov_b32_e32 v138, 0xf149f2ca
	v_mov_b32_e32 v137, 0xf149f2ca
	v_mov_b32_e32 v136, 0xf149f2ca
	v_mov_b32_e32 v135, 0xf149f2ca
	v_mov_b32_e32 v134, 0xf149f2ca
	v_mov_b32_e32 v133, 0xf149f2ca
	v_mov_b32_e32 v132, 0xf149f2ca
	v_mov_b32_e32 v131, 0xf149f2ca
	v_mov_b32_e32 v130, 0xf149f2ca
	v_mov_b32_e32 v129, 0xf149f2ca
	v_mov_b32_e32 v128, 0xf149f2ca
	v_mov_b32_e32 v127, 0xf149f2ca
	v_mov_b32_e32 v126, 0xf149f2ca
	v_mov_b32_e32 v125, 0xf149f2ca
	v_mov_b32_e32 v124, 0xf149f2ca
	v_mov_b32_e32 v123, 0xf149f2ca
	v_mov_b32_e32 v122, 0xf149f2ca
	v_mov_b32_e32 v121, 0xf149f2ca
	v_mov_b32_e32 v120, 0xf149f2ca
	v_mov_b32_e32 v119, 0xf149f2ca
	v_mov_b32_e32 v118, 0xf149f2ca
	v_mov_b32_e32 v117, 0xf149f2ca
	v_mov_b32_e32 v116, 0xf149f2ca
	v_mov_b32_e32 v115, 0xf149f2ca
	v_mov_b32_e32 v114, 0xf149f2ca
	v_mov_b32_e32 v113, 0xf149f2ca
	v_mov_b32_e32 v112, 0xf149f2ca
	s_and_b64 vcc, exec, s[54:55]
	s_cbranch_vccnz .LBB0_1444
	s_branch .LBB0_1445

.LBB0_1448:
	ds_read_b64_tr_b16 v[114:115], v162 offset:0x200
	ds_read_b64_tr_b16 v[116:117], v162 offset:0xa00
	ds_read_b64_tr_b16 v[118:119], v162 offset:0x1200
	ds_read_b64_tr_b16 v[120:121], v162 offset:0x1a00
	ds_read_b64_tr_b16 v[122:123], v162 offset:0x2200
	ds_read_b64_tr_b16 v[124:125], v162 offset:0x2a00
	ds_read_b64_tr_b16 v[130:131], v162 offset:0x3200
	ds_read_b64_tr_b16 v[132:133], v162 offset:0x3a00
	s_waitcnt lgkmcnt(8)
	v_exp_f32_e32 v96, v128
	v_mfma_f32_32x32x16_bf16 v[64:79], v[166:169], v[182:185], v[64:79]
	v_exp_f32_e32 v80, v112
	v_mfma_f32_32x32x16_bf16 v[64:79], v[12:15], v[178:181], v[64:79]
	v_exp_f32_e32 v97, v97
	v_exp_f32_e32 v81, v81
	v_mfma_f32_32x32x16_bf16 v[64:79], v[8:11], v[174:177], v[64:79]
	v_exp_f32_e32 v98, v98
	v_exp_f32_e32 v82, v82
	v_mfma_f32_32x32x16_bf16 v[64:79], v[4:7], v[170:173], v[64:79]
	v_exp_f32_e32 v99, v99
	v_exp_f32_e32 v83, v83
	ds_read_b64_tr_b16 v[126:127], v162 offset:0x400
	ds_read_b64_tr_b16 v[128:129], v162 offset:0xc00
	ds_read_b64_tr_b16 v[134:135], v162 offset:0x1400
	ds_read_b64_tr_b16 v[136:137], v162 offset:0x1c00
	ds_read_b64_tr_b16 v[138:139], v162 offset:0x2400
	ds_read_b64_tr_b16 v[140:141], v162 offset:0x2c00
	ds_read_b64_tr_b16 v[170:171], v162 offset:0x3400
	ds_read_b64_tr_b16 v[172:173], v162 offset:0x3c00
	s_waitcnt lgkmcnt(8)
	s_nop 0
	v_exp_f32_e32 v100, v100
	v_mfma_f32_32x32x16_bf16 v[48:63], v[166:169], v[114:117], v[48:63]
	v_exp_f32_e32 v84, v84
	v_mfma_f32_32x32x16_bf16 v[48:63], v[12:15], v[118:121], v[48:63]
	v_exp_f32_e32 v101, v101
	v_exp_f32_e32 v85, v85
	v_mfma_f32_32x32x16_bf16 v[48:63], v[8:11], v[122:125], v[48:63]
	v_exp_f32_e32 v102, v102
	v_exp_f32_e32 v86, v86
	v_mfma_f32_32x32x16_bf16 v[48:63], v[4:7], v[130:133], v[48:63]
	v_exp_f32_e32 v103, v103
	v_exp_f32_e32 v87, v87
	ds_read_b64_tr_b16 v[112:113], v162 offset:0x600
	ds_read_b64_tr_b16 v[114:115], v162 offset:0xe00
	ds_read_b64_tr_b16 v[116:117], v162 offset:0x1600
	ds_read_b64_tr_b16 v[118:119], v162 offset:0x1e00
	ds_read_b64_tr_b16 v[120:121], v162 offset:0x2600
	ds_read_b64_tr_b16 v[122:123], v162 offset:0x2e00
	ds_read_b64_tr_b16 v[130:131], v162 offset:0x3600
	ds_read_b64_tr_b16 v[132:133], v162 offset:0x3e00
	s_waitcnt lgkmcnt(8)
	s_nop 0
	v_exp_f32_e32 v104, v104
	v_mfma_f32_32x32x16_bf16 v[32:47], v[166:169], v[126:129], v[32:47]
	v_exp_f32_e32 v88, v88
	v_mfma_f32_32x32x16_bf16 v[32:47], v[12:15], v[134:137], v[32:47]
	v_exp_f32_e32 v105, v105
	v_exp_f32_e32 v89, v89
	v_mfma_f32_32x32x16_bf16 v[32:47], v[8:11], v[138:141], v[32:47]
	v_exp_f32_e32 v106, v106
	v_exp_f32_e32 v90, v90
	v_mfma_f32_32x32x16_bf16 v[32:47], v[4:7], v[170:173], v[32:47]
	v_exp_f32_e32 v107, v107
	v_exp_f32_e32 v91, v91
	s_waitcnt lgkmcnt(0)
	s_nop 0
	v_exp_f32_e32 v108, v108
	v_mfma_f32_32x32x16_bf16 v[16:31], v[166:169], v[112:115], v[16:31]
	v_exp_f32_e32 v92, v92
	v_mfma_f32_32x32x16_bf16 v[16:31], v[12:15], v[116:119], v[16:31]
	v_exp_f32_e32 v109, v109
	v_exp_f32_e32 v93, v93
	v_mfma_f32_32x32x16_bf16 v[16:31], v[8:11], v[120:123], v[16:31]
	v_exp_f32_e32 v110, v110
	v_exp_f32_e32 v94, v94
	v_mfma_f32_32x32x16_bf16 v[16:31], v[4:7], v[130:133], v[16:31]
	v_exp_f32_e32 v111, v111
	v_exp_f32_e32 v95, v95
	v_cmp_gt_f32_e32 vcc, 1.0, v196
	s_cbranch_vccz .LBB0_1452
.Lresc_even_blk:
	s_and_saveexec_b64 s[54:55], s[4:5]
	ds_write_b32 v213, v196 offset:128
	s_or_b64 exec, exec, s[54:55]
	s_waitcnt lgkmcnt(0)
	ds_read_b128 v[4:7], v212 offset:224
	ds_read_b128 v[8:11], v212 offset:192
	ds_read_b128 v[12:15], v212 offset:160
	ds_read_b128 v[112:115], v212 offset:128
	s_waitcnt lgkmcnt(0)
	v_pk_mul_f32 v[78:79], v[78:79], v[6:7]
	v_pk_mul_f32 v[74:75], v[74:75], v[10:11]
	v_pk_mul_f32 v[70:71], v[70:71], v[14:15]
	v_pk_mul_f32 v[66:67], v[66:67], v[114:115]
	v_pk_mul_f32 v[76:77], v[76:77], v[4:5]
	v_pk_mul_f32 v[72:73], v[72:73], v[8:9]
	v_pk_mul_f32 v[68:69], v[68:69], v[12:13]
	v_pk_mul_f32 v[64:65], v[64:65], v[112:113]
	v_pk_mul_f32 v[62:63], v[6:7], v[62:63]
	v_pk_mul_f32 v[58:59], v[10:11], v[58:59]
	v_pk_mul_f32 v[54:55], v[14:15], v[54:55]
	v_pk_mul_f32 v[50:51], v[114:115], v[50:51]
	v_pk_mul_f32 v[60:61], v[4:5], v[60:61]
	v_pk_mul_f32 v[56:57], v[8:9], v[56:57]
	v_pk_mul_f32 v[52:53], v[12:13], v[52:53]
	v_pk_mul_f32 v[48:49], v[112:113], v[48:49]
	v_pk_mul_f32 v[46:47], v[6:7], v[46:47]
	v_pk_mul_f32 v[42:43], v[10:11], v[42:43]
	v_pk_mul_f32 v[38:39], v[14:15], v[38:39]
	v_pk_mul_f32 v[34:35], v[114:115], v[34:35]
	v_pk_mul_f32 v[44:45], v[4:5], v[44:45]
	v_pk_mul_f32 v[40:41], v[8:9], v[40:41]
	v_pk_mul_f32 v[36:37], v[12:13], v[36:37]
	v_pk_mul_f32 v[32:33], v[112:113], v[32:33]
	v_pk_mul_f32 v[30:31], v[6:7], v[30:31]
	v_pk_mul_f32 v[26:27], v[10:11], v[26:27]
	v_pk_mul_f32 v[22:23], v[14:15], v[22:23]
	v_pk_mul_f32 v[18:19], v[114:115], v[18:19]
	v_pk_mul_f32 v[28:29], v[4:5], v[28:29]
	v_pk_mul_f32 v[24:25], v[8:9], v[24:25]
	v_pk_mul_f32 v[20:21], v[12:13], v[20:21]
	v_pk_mul_f32 v[16:17], v[112:113], v[16:17]
	s_branch .LBB0_1452
